# seams: team+xcd barrier early L1 invalidate and concurrent first poll; GEMM prologue issues all 14 LDS-DMA pieces (K-tiles 0 and 1) before the first wait, stagger barrier moved below them
# baseline (speedup 1.0000x reference)
; #define PG8_STAGE(bufoff, gbase, voff) do { const unsigned long long gb_ = (unsigned long long)(gbase); _Pragma("unroll") for (int _i = 0; _i < 2; ++_i) { unsigned keep_; \
;         asm volatile("s_mov_b32 m0, %2\n\ts_nop 0\n\tglobal_load_lds_dwordx4 %0, %1" : : "v"((voff)[_i]), "s"(gb_), "s"((unsigned)(size_t)(lds + (bufoff) + ldsw + _i * 8192)) : "memory", "m0"); (void)keep_; } } while (0)
; #define PG8_WAIT_V(n) asm volatile("s_waitcnt vmcnt(" #n ")" ::: "memory")
; #define PG8_BAR __builtin_amdgcn_s_barrier()
; template <class Epi, class Sched, bool ALIGN_EPI = false, bool SP2 = false>
; __device__ __forceinline__ void gemm_phase(PG8_LAS unsigned char* lds, const Gemm g, const Sched& S, const Epi& E) {
;     ...
;     const unsigned ldsw = (unsigned)wid * 1024u;
;     const int aoff = lds_byte(wr * 64 + fr, fq * 8), boff = lds_byte(wc * 32 + fr, fq * 8);
;     ...
;     if constexpr (SP2) {
;         PG8_STAGE(PG8_SB(0, 0), cB, voffB); PG8_STAGE(PG8_SB(0, 1), cB + hstepB, voffB); PG8_STAGE(PG8_SA(0, 0), cA, voffA); PG8_STAGE(PG8_SA(0, 1), cA + hstepA, voffA);
;         if (wr == 1) PG8_BAR;
;         PG8_WAIT_V(2); PG8_BAR;
;         PG8_STAGE(PG8_SB(1, 0), cB + kstep, voffB); PG8_STAGE(PG8_SA(1, 0), cA + kstep, voffA); PG8_STAGE(PG8_SB(1, 1), cB + hstepB + kstep, voffB);
;         PG8_WAIT_V(6); PG8_BAR;
.LBB0_365:
	v_and_b32_e32 v1, 15, v200
	v_lshlrev_b32_e32 v2, 1, v0
	v_lshlrev_b32_e32 v4, 2, v200
	s_lshl_b32 s22, s0, 6
	v_lshl_or_b32 v3, v1, 6, v2
	s_lshl_b32 s0, s0, 13
	v_and_b32_e32 v4, 32, v4
	v_bitop3_b32 v3, v3, s0, v4 bitop3:0xde
	s_lshl_b32 s0, s1, 5
	s_and_b32 s23, s0, 0x60
	v_lshlrev_b32_e32 v5, 6, v200
	s_movk_i32 s0, 0x3c0
	v_and_or_b32 v2, v5, s0, v2
	s_lshl_b32 s0, s23, 7
	s_add_u32 s54, s74, 0xe000000
	s_addc_u32 s55, s75, 0
	v_or_b32_e32 v128, s22, v1
	v_bitop3_b32 v2, s0, v2, v4 bitop3:0xf6
	s_mov_b32 s24, 0x160000
	s_and_b64 s[0:1], s[20:21], exec
	s_cselect_b32 s56, s24, 0x200000
	s_add_u32 s0, s36, 0x80
	v_mov_b32_e32 v131, 0
	v_or_b32_e32 v130, 16, v128
	s_addc_u32 s1, s37, 0
	s_add_i32 s57, s35, 0x18000
	s_mov_b32 m0, s57
	s_nop 0
	global_load_lds_dwordx4 v161, s[0:1]
	s_add_i32 s58, s35, 0x1a000
	v_lshlrev_b64 v[134:135], 8, v[130:131]
	v_or_b32_e32 v130, 32, v128
	s_mov_b32 m0, s58
	s_nop 0
	global_load_lds_dwordx4 v165, s[0:1]
	s_add_u32 s0, s8, 0x80
	v_lshlrev_b64 v[136:137], 8, v[130:131]
	v_or_b32_e32 v130, 48, v128
	s_addc_u32 s1, s9, 0
	s_add_i32 s59, s35, 0x8000
	s_mov_b32 m0, s59
	s_nop 0
	global_load_lds_dwordx4 v159, s[0:1]
	s_add_i32 s60, s35, 0xa000
	v_lshlrev_b64 v[138:139], 8, v[130:131]
	v_add_u32_e32 v130, 0x80, v128
	s_mov_b32 m0, s60
	s_nop 0
	global_load_lds_dwordx4 v163, s[0:1]
	s_add_u32 s0, s36, 0x80080
	v_lshlrev_b64 v[140:141], 8, v[130:131]
	v_add_u32_e32 v130, 0x90, v128
	s_addc_u32 s1, s37, 0
	s_add_i32 s61, s35, 0x1c000
	s_mov_b32 m0, s61
	s_nop 0
	global_load_lds_dwordx4 v161, s[0:1]
	v_lshlrev_b64 v[142:143], 8, v[130:131]
	v_add_u32_e32 v130, 0xa0, v128
	s_add_i32 s62, s35, 0x1e000
	s_mov_b32 m0, s62
	s_nop 0
	global_load_lds_dwordx4 v165, s[0:1]
	v_mov_b32_e32 v4, 0xcf
	v_lshlrev_b64 v[144:145], 8, v[130:131]
	v_add_u32_e32 v130, 0xb0, v128
	s_cmp_eq_u64 s[18:19], 0
	s_cbranch_scc1 .Lstag_skip_15
	s_barrier
.Lstag_skip_15:
	s_waitcnt vmcnt(8)
	s_barrier
	s_waitcnt vmcnt(6)
	s_add_i32 s63, s35, 0xc000
	v_bitop3_b32 v1, s22, v4, v1 bitop3:0xc8
	v_mov_b32_e32 v129, v131
	v_lshlrev_b64 v[146:147], 8, v[130:131]
	v_lshlrev_b32_e32 v130, 2, v0
	s_cmpk_lt_u32 s16, 0x100
	v_lshlrev_b64 v[132:133], 8, v[128:129]
	v_lshl_add_u64 v[148:149], s[6:7], 0, v[130:131]
	v_lshl_add_u32 v129, v1, 2, s5
	v_add_u32_e32 v1, 0, v2
	v_lshlrev_b32_e32 v130, 1, v0
	v_mbcnt_lo_u32_b32 v0, -1, 0
	s_cselect_b64 s[20:21], -1, 0
	s_add_i32 s64, s35, 0xe000
	s_ashr_i32 s65, s4, 31
	s_ashr_i32 s66, s2, 31
	v_mov_b64_e32 v[150:151], 0xb00
	v_mov_b64_e32 v[152:153], 0xaff
	s_movk_i32 s67, 0x161
	v_add_u32_e32 v167, 0x10000, v1
	v_add_u32_e32 v169, 0x14000, v1
	v_add_u32_e32 v172, 0, v3
	v_add_u32_e32 v173, 0x18000, v1
	v_add_u32_e32 v174, 0x1c000, v1
	v_mov_b32_e32 v175, 0x358637bd
	s_lshl_b32 s16, s23, 1
	v_mbcnt_hi_u32_b32 v176, -1, v0
	s_mov_b32 s68, s17
	s_barrier
	s_branch .LBB0_368

; __device__ __forceinline__ unsigned xb_add(unsigned* p, unsigned v) { return __hip_atomic_fetch_add(p, v, __ATOMIC_RELAXED, __HIP_MEMORY_SCOPE_AGENT); }
; __device__ __forceinline__ void xcd_barrier(const XcdBarrier& b) {
;     ...
;     if (threadIdx.x == 0) {
;         unsigned* bar = b.bar;
;         __builtin_amdgcn_s_waitcnt(0);
;         unsigned nloc = b.st[0], nx = b.st[1];
;         if (nloc == 0u) { xcd_barrier_complete(bar, b.x, nloc, nx); b.st[0] = nloc; b.st[1] = nx; }
;         const unsigned old = xb_add(&bar[XB_XSUB(b.x)], 1u);
;         const unsigned gen = old / nloc;
;         if (old + 1u == (gen + 1u) * nloc) {
.LBB0_431:
	s_mov_b64 s[0:1], exec
	s_lshl_b32 s4, s3, 8
	v_mbcnt_lo_u32_b32 v1, s0, 0
	s_add_u32 s12, s74, s4
	v_mbcnt_hi_u32_b32 v1, s1, v1
	s_addc_u32 s13, s75, 0
	v_cmp_eq_u32_e32 vcc, 0, v1
	s_and_saveexec_b64 s[14:15], vcc
	s_cbranch_execz .LBB0_433
	s_bcnt1_i32_b64 s0, s[0:1]
	v_mov_b32_e32 v3, 0x1000
	v_mov_b32_e32 v4, s0
	global_atomic_add v3, v3, v4, s[12:13] offset:1024 sc0
	buffer_inv sc1

; __device__ __forceinline__ unsigned xb_ld(unsigned* p)              { return __hip_atomic_load(p, __ATOMIC_RELAXED, __HIP_MEMORY_SCOPE_AGENT); }
; __device__ __forceinline__ unsigned xb_add(unsigned* p, unsigned v) { return __hip_atomic_fetch_add(p, v, __ATOMIC_RELAXED, __HIP_MEMORY_SCOPE_AGENT); }
; #define XB_SPIN(cond, bar) do { unsigned _sp = 0; while (cond) { __builtin_amdgcn_s_sleep(1); \
;     if ((++_sp & 255u) == 0u) { if (xb_ld(&(bar)[XB_TMO])) break; if (_sp > XB_SPIN_CAP) { atomicAdd(&(bar)[XB_TMO], 1u); break; } } } } while (0)
; __device__ __forceinline__ void xcd_barrier(const XcdBarrier& b) {
;     ...
;         if (old + 1u == (gen + 1u) * nloc) {
;             __builtin_amdgcn_fence(__ATOMIC_RELEASE, "agent");
;             asm volatile("s_waitcnt vmcnt(0)" ::: "memory");
;             const unsigned og = xb_add(&bar[XB_TOP], 1u);
;             const unsigned tg = og / nx;
;             if (og + 1u == (tg + 1u) * nx) xb_add(&bar[XB_TOPGEN], 1u);
;             else XB_SPIN(xb_ld(&bar[XB_TOPGEN]) == tg, bar);
;             __builtin_amdgcn_fence(__ATOMIC_ACQUIRE, "agent");
;             xb_add(&bar[XB_XGEN(b.x)], 1u);
;             asm volatile("s_waitcnt vmcnt(0)" ::: "memory");
;         } else {
;             XB_SPIN(xb_ld(&bar[XB_XGEN(b.x)]) == gen, bar);
;             __builtin_amdgcn_fence(__ATOMIC_ACQUIRE, "agent");
;             asm volatile("s_waitcnt vmcnt(0)" ::: "memory");
;         }
.LBB0_443:
	s_or_b64 exec, exec, s[18:19]
	s_xor_b64 s[4:5], s[20:21], -1
	s_and_saveexec_b64 s[16:17], s[4:5]
	s_xor_b64 s[16:17], exec, s[16:17]
	s_cbranch_execz .LBB0_446
	s_mov_b64 s[16:17], exec
	v_mbcnt_lo_u32_b32 v0, s16, 0
	v_mbcnt_hi_u32_b32 v0, s17, v0
	v_cmp_eq_u32_e32 vcc, 0, v0
	s_and_b64 s[4:5], exec, vcc
	s_mov_b64 exec, s[4:5]
	s_cbranch_execz .LBB0_446
	s_bcnt1_i32_b64 s4, s[16:17]
	v_mov_b32_e32 v0, 0
	v_mov_b32_e32 v1, s4
	global_atomic_add v0, v1, s[74:75] offset:512
.LBB0_446:
	s_or_b64 exec, exec, s[0:1]
	s_waitcnt vmcnt(0)
	s_waitcnt vmcnt(0)
.LBB0_447:
	s_andn2_saveexec_b64 s[0:1], s[14:15]
	s_cbranch_execz .LBB0_467
	s_mov_b64 s[0:1], exec
	buffer_wbl2 sc1
	s_waitcnt lgkmcnt(0)
	s_waitcnt vmcnt(0)
	v_mbcnt_lo_u32_b32 v1, s0, 0
	v_mbcnt_hi_u32_b32 v1, s1, v1
	v_cmp_eq_u32_e32 vcc, 0, v1
	s_and_saveexec_b64 s[14:15], vcc
	s_cbranch_execz .LBB0_450
	s_bcnt1_i32_b64 s0, s[0:1]
	v_mov_b32_e32 v2, 0x3000
	v_mov_b32_e32 v3, s0
	global_atomic_add v2, v2, v3, s[74:75] offset:1024 sc0

; __device__ __forceinline__ unsigned xb_ld(unsigned* p)              { return __hip_atomic_load(p, __ATOMIC_RELAXED, __HIP_MEMORY_SCOPE_AGENT); }
; __device__ __forceinline__ unsigned xb_add(unsigned* p, unsigned v) { return __hip_atomic_fetch_add(p, v, __ATOMIC_RELAXED, __HIP_MEMORY_SCOPE_AGENT); }
; #define XB_SPIN(cond, bar) do { unsigned _sp = 0; while (cond) { __builtin_amdgcn_s_sleep(1); \
;     if ((++_sp & 255u) == 0u) { if (xb_ld(&(bar)[XB_TMO])) break; if (_sp > XB_SPIN_CAP) { atomicAdd(&(bar)[XB_TMO], 1u); break; } } } } while (0)
; __device__ __forceinline__ void xcd_barrier(const XcdBarrier& b) {
;     ...
;             const unsigned og = xb_add(&bar[XB_TOP], 1u);
;             const unsigned tg = og / nx;
;             if (og + 1u == (tg + 1u) * nx) xb_add(&bar[XB_TOPGEN], 1u);
;             else XB_SPIN(xb_ld(&bar[XB_TOPGEN]) == tg, bar);
;             __builtin_amdgcn_fence(__ATOMIC_ACQUIRE, "agent");
;             xb_add(&bar[XB_XGEN(b.x)], 1u);
;             asm volatile("s_waitcnt vmcnt(0)" ::: "memory");
.LBB0_464:
	s_or_b64 exec, exec, s[0:1]
	s_mov_b64 s[0:1], exec
	v_mbcnt_lo_u32_b32 v0, s0, 0
	v_mbcnt_hi_u32_b32 v0, s1, v0
	v_cmp_eq_u32_e32 vcc, 0, v0
	s_waitcnt vmcnt(0)
	s_and_saveexec_b64 s[14:15], vcc
	s_cbranch_execz .LBB0_466
	s_bcnt1_i32_b64 s0, s[0:1]
	v_mov_b32_e32 v0, 0x2000
	v_mov_b32_e32 v1, s0
	global_atomic_add v0, v1, s[12:13] offset:1024

; #define PG8_STAGE(bufoff, gbase, voff) do { const unsigned long long gb_ = (unsigned long long)(gbase); _Pragma("unroll") for (int _i = 0; _i < 2; ++_i) { unsigned keep_; \
;         asm volatile("s_mov_b32 m0, %2\n\ts_nop 0\n\tglobal_load_lds_dwordx4 %0, %1" : : "v"((voff)[_i]), "s"(gb_), "s"((unsigned)(size_t)(lds + (bufoff) + ldsw + _i * 8192)) : "memory", "m0"); (void)keep_; } } while (0)
; #define PG8_WAIT_V(n) asm volatile("s_waitcnt vmcnt(" #n ")" ::: "memory")
; #define PG8_BAR __builtin_amdgcn_s_barrier()
; template <class Epi, class Sched, bool ALIGN_EPI = false, bool SP2 = false>
; __device__ __forceinline__ void gemm_phase(PG8_LAS unsigned char* lds, const Gemm g, const Sched& S, const Epi& E) {
;     ...
;     const unsigned ldsw = (unsigned)wid * 1024u;
;     const int aoff = lds_byte(wr * 64 + fr, fq * 8), boff = lds_byte(wc * 32 + fr, fq * 8);
;     ...
;     if constexpr (SP2) {
;         PG8_STAGE(PG8_SB(0, 0), cB, voffB); PG8_STAGE(PG8_SB(0, 1), cB + hstepB, voffB); PG8_STAGE(PG8_SA(0, 0), cA, voffA); PG8_STAGE(PG8_SA(0, 1), cA + hstepA, voffA);
;         if (wr == 1) PG8_BAR;
;         PG8_WAIT_V(2); PG8_BAR;
;         PG8_STAGE(PG8_SB(1, 0), cB + kstep, voffB); PG8_STAGE(PG8_SA(1, 0), cA + kstep, voffA); PG8_STAGE(PG8_SB(1, 1), cB + hstepB + kstep, voffB);
;         PG8_WAIT_V(6); PG8_BAR;
.LBB0_497:
	v_bfe_u32 v2, v200, 4, 2
	s_add_u32 s20, s74, 0x400000
	v_and_b32_e32 v1, 15, v200
	v_lshlrev_b32_e32 v0, 4, v2
	v_lshlrev_b32_e32 v3, 2, v200
	s_addc_u32 s21, s75, 0
	s_and_b32 s49, s0, 3
	v_lshl_or_b32 v144, s1, 6, v1
	v_lshl_or_b32 v1, v1, 6, v0
	s_lshl_b32 s0, s1, 13
	v_and_b32_e32 v3, 32, v3
	v_bitop3_b32 v5, v1, s0, v3 bitop3:0xde
	v_lshlrev_b32_e32 v1, 6, v200
	s_movk_i32 s0, 0x3c0
	v_and_or_b32 v1, v1, s0, v0
	s_lshl_b32 s0, s49, 12
	s_waitcnt vmcnt(23)
	v_bitop3_b32 v6, s0, v1, v3 bitop3:0xf6
	s_add_u32 s0, s28, 0x80
	s_addc_u32 s1, s29, 0
	s_add_i32 s50, s41, 0x18000
	s_mov_b32 m0, s50
	s_nop 0
	global_load_lds_dwordx4 v177, s[0:1]
	s_add_i32 s51, s41, 0x1a000
	s_mov_b32 m0, s51
	s_nop 0
	global_load_lds_dwordx4 v179, s[0:1]
	s_add_u32 s0, s26, 0x80
	s_addc_u32 s1, s27, 0
	s_add_i32 s52, s41, 0x8000
	s_mov_b32 m0, s52
	s_nop 0
	global_load_lds_dwordx4 v176, s[0:1]
	s_add_i32 s53, s41, 0xa000
	s_mov_b32 m0, s53
	s_nop 0
	global_load_lds_dwordx4 v178, s[0:1]
	s_add_u32 s0, s28, 0x160080
	s_addc_u32 s1, s29, 0
	s_add_i32 s54, s41, 0x1c000
	s_add_i32 s55, s41, 0x1e000
	s_add_i32 s56, s41, 0xc000
	v_mov_b32_e32 v145, 0
	v_lshlrev_b32_e32 v4, 3, v2
	s_mov_b32 m0, s54
	s_nop 0
	global_load_lds_dwordx4 v177, s[0:1]
	s_cmpk_lt_u32 s8, 0x100
	v_cmp_eq_u32_e64 s[6:7], 0, v2
	v_or_b32_e32 v2, 16, v144
	v_mov_b32_e32 v3, v145
	s_mov_b32 m0, s55
	s_nop 0
	global_load_lds_dwordx4 v179, s[0:1]
	s_cselect_b64 s[22:23], -1, 0
	v_lshlrev_b64 v[148:149], 9, v[2:3]
	v_or_b32_e32 v2, 32, v144
	s_add_i32 s57, s41, 0xe000
	s_ashr_i32 s58, s4, 31
	s_ashr_i32 s59, s2, 31
	s_lshl_b32 s0, s49, 6
	v_lshlrev_b64 v[150:151], 9, v[2:3]
	v_or_b32_e32 v2, 48, v144
	s_add_u32 s0, s74, s0
	v_lshlrev_b64 v[152:153], 9, v[2:3]
	v_add_u32_e32 v2, 0x80, v144
	s_addc_u32 s1, s75, 0
	v_mov_b32_e32 v1, v145
	v_lshlrev_b64 v[154:155], 9, v[2:3]
	v_add_u32_e32 v2, 0x90, v144
	v_lshl_add_u64 v[0:1], s[0:1], 0, v[0:1]
	s_mov_b64 s[0:1], 0x6000000
	s_cmp_eq_u64 s[18:19], 0
	s_cbranch_scc1 .Lstag_skip_14
	s_barrier
.Lstag_skip_14:
	s_waitcnt vmcnt(8)
	s_barrier
	s_waitcnt vmcnt(6)
	v_lshlrev_b64 v[156:157], 9, v[2:3]
	v_add_u32_e32 v2, 0xa0, v144
	v_lshl_add_u64 v[162:163], v[0:1], 0, s[0:1]
	v_add_u32_e32 v0, 0, v6
	v_lshlrev_b64 v[158:159], 9, v[2:3]
	v_add_u32_e32 v2, 0xb0, v144
	v_add_u32_e32 v180, 0x10000, v0
	v_add_u32_e32 v181, 0x14000, v0
	v_add_u32_e32 v183, 0x18000, v0
	v_add_u32_e32 v184, 0x1c000, v0
	v_mbcnt_lo_u32_b32 v0, -1, 0
	v_lshlrev_b64 v[146:147], 9, v[144:145]
	v_lshlrev_b64 v[160:161], 9, v[2:3]
	v_lshl_or_b32 v145, s49, 5, v4
	v_mov_b64_e32 v[164:165], 0x200
	v_mov_b64_e32 v[166:167], 0x1ff
	v_add_u32_e32 v182, 0, v5
	v_mbcnt_hi_u32_b32 v185, -1, v0
	s_mov_b32 s60, 0
	s_barrier
	s_branch .LBB0_500

; __device__ __forceinline__ unsigned xb_ld(unsigned* p)              { return __hip_atomic_load(p, __ATOMIC_RELAXED, __HIP_MEMORY_SCOPE_AGENT); }
; __device__ __forceinline__ unsigned xb_add(unsigned* p, unsigned v) { return __hip_atomic_fetch_add(p, v, __ATOMIC_RELAXED, __HIP_MEMORY_SCOPE_AGENT); }
; #define XB_SPIN(cond, bar) do { unsigned _sp = 0; while (cond) { __builtin_amdgcn_s_sleep(1); \
;     if ((++_sp & 255u) == 0u) { if (xb_ld(&(bar)[XB_TMO])) break; if (_sp > XB_SPIN_CAP) { atomicAdd(&(bar)[XB_TMO], 1u); break; } } } } while (0)
; __device__ __forceinline__ void xcd_barrier(const XcdBarrier& b) {
;     ...
;         if (old + 1u == (gen + 1u) * nloc) {
;             __builtin_amdgcn_fence(__ATOMIC_RELEASE, "agent");
;             asm volatile("s_waitcnt vmcnt(0)" ::: "memory");
;             const unsigned og = xb_add(&bar[XB_TOP], 1u);
;             const unsigned tg = og / nx;
;             if (og + 1u == (tg + 1u) * nx) xb_add(&bar[XB_TOPGEN], 1u);
;             else XB_SPIN(xb_ld(&bar[XB_TOPGEN]) == tg, bar);
;             __builtin_amdgcn_fence(__ATOMIC_ACQUIRE, "agent");
;             xb_add(&bar[XB_XGEN(b.x)], 1u);
;             asm volatile("s_waitcnt vmcnt(0)" ::: "memory");
;         } else {
;             XB_SPIN(xb_ld(&bar[XB_XGEN(b.x)]) == gen, bar);
;             __builtin_amdgcn_fence(__ATOMIC_ACQUIRE, "agent");
;             asm volatile("s_waitcnt vmcnt(0)" ::: "memory");
;         }
.LBB0_564:
	s_or_b64 exec, exec, s[18:19]
	s_xor_b64 s[4:5], s[20:21], -1
	s_and_saveexec_b64 s[16:17], s[4:5]
	s_xor_b64 s[16:17], exec, s[16:17]
	s_cbranch_execz .LBB0_567
	s_mov_b64 s[16:17], exec
	v_mbcnt_lo_u32_b32 v0, s16, 0
	v_mbcnt_hi_u32_b32 v0, s17, v0
	v_cmp_eq_u32_e32 vcc, 0, v0
	s_and_b64 s[4:5], exec, vcc
	s_mov_b64 exec, s[4:5]
	s_cbranch_execz .LBB0_567
	s_bcnt1_i32_b64 s4, s[16:17]
	v_mov_b32_e32 v0, 0
	v_mov_b32_e32 v1, s4
	global_atomic_add v0, v1, s[74:75] offset:512
.LBB0_567:
	s_or_b64 exec, exec, s[0:1]
	s_waitcnt vmcnt(0)
	s_waitcnt vmcnt(0)
.LBB0_568:
	s_andn2_saveexec_b64 s[0:1], s[14:15]
	s_cbranch_execz .LBB0_588
	s_mov_b64 s[0:1], exec
	buffer_wbl2 sc1
	s_waitcnt lgkmcnt(0)
	s_waitcnt vmcnt(0)
	v_mbcnt_lo_u32_b32 v1, s0, 0
	v_mbcnt_hi_u32_b32 v1, s1, v1
	v_cmp_eq_u32_e32 vcc, 0, v1
	s_and_saveexec_b64 s[14:15], vcc
	s_cbranch_execz .LBB0_571
	s_bcnt1_i32_b64 s0, s[0:1]
	v_mov_b32_e32 v2, 0x3000
	v_mov_b32_e32 v3, s0
	global_atomic_add v2, v2, v3, s[74:75] offset:1024 sc0

; #define PG8_STAGE(bufoff, gbase, voff) do { const unsigned long long gb_ = (unsigned long long)(gbase); _Pragma("unroll") for (int _i = 0; _i < 2; ++_i) { unsigned keep_; \
;         asm volatile("s_mov_b32 m0, %2\n\ts_nop 0\n\tglobal_load_lds_dwordx4 %0, %1" : : "v"((voff)[_i]), "s"(gb_), "s"((unsigned)(size_t)(lds + (bufoff) + ldsw + _i * 8192)) : "memory", "m0"); (void)keep_; } } while (0)
; #define PG8_WAIT_V(n) asm volatile("s_waitcnt vmcnt(" #n ")" ::: "memory")
; #define PG8_BAR __builtin_amdgcn_s_barrier()
; template <class Epi, class Sched, bool ALIGN_EPI = false, bool SP2 = false>
; __device__ __forceinline__ void gemm_phase(PG8_LAS unsigned char* lds, const Gemm g, const Sched& S, const Epi& E) {
;     ...
;     const unsigned ldsw = (unsigned)wid * 1024u;
;     const int aoff = lds_byte(wr * 64 + fr, fq * 8), boff = lds_byte(wc * 32 + fr, fq * 8);
;     ...
;     if constexpr (SP2) {
;         PG8_STAGE(PG8_SB(0, 0), cB, voffB); PG8_STAGE(PG8_SB(0, 1), cB + hstepB, voffB); PG8_STAGE(PG8_SA(0, 0), cA, voffA); PG8_STAGE(PG8_SA(0, 1), cA + hstepA, voffA);
;         if (wr == 1) PG8_BAR;
;         PG8_WAIT_V(2); PG8_BAR;
;         PG8_STAGE(PG8_SB(1, 0), cB + kstep, voffB); PG8_STAGE(PG8_SA(1, 0), cA + kstep, voffA); PG8_STAGE(PG8_SB(1, 1), cB + hstepB + kstep, voffB);
;         PG8_WAIT_V(6); PG8_BAR;
.LBB0_622:
	v_bfe_u32 v2, v200, 4, 2
	v_and_b32_e32 v1, 15, v200
	v_lshlrev_b32_e32 v3, 4, v2
	v_lshlrev_b32_e32 v5, 2, v200
	s_and_b32 s20, s0, 3
	v_lshl_or_b32 v4, v1, 6, v3
	s_lshl_b32 s0, s1, 13
	v_and_b32_e32 v5, 32, v5
	v_bitop3_b32 v4, v4, s0, v5 bitop3:0xde
	s_waitcnt vmcnt(23)
	v_lshlrev_b32_e32 v6, 6, v200
	s_movk_i32 s0, 0x3c0
	s_lshl_b32 s5, s1, 6
	s_lshl_b32 s68, s20, 5
	v_and_or_b32 v3, v6, s0, v3
	s_lshl_b32 s0, s20, 12
	s_add_u32 s69, s74, 0xe000000
	s_addc_u32 s70, s75, 0
	s_add_u32 s22, s74, 0x600000
	v_or_b32_e32 v128, s5, v1
	s_addc_u32 s23, s75, 0
	v_bitop3_b32 v3, s0, v3, v5 bitop3:0xf6
	s_add_u32 s0, s52, 0x80
	v_mov_b32_e32 v131, 0
	v_or_b32_e32 v130, 16, v128
	s_addc_u32 s1, s53, 0
	s_add_i32 s71, s39, 0x18000
	s_mov_b32 m0, s71
	s_nop 0
	global_load_lds_dwordx4 v161, s[0:1]
	s_add_i32 s72, s39, 0x1a000
	v_lshlrev_b64 v[134:135], 9, v[130:131]
	v_or_b32_e32 v130, 32, v128
	s_mov_b32 m0, s72
	s_nop 0
	global_load_lds_dwordx4 v169, s[0:1]
	s_add_u32 s0, s10, 0x80
	v_lshlrev_b64 v[136:137], 9, v[130:131]
	v_or_b32_e32 v130, 48, v128
	s_addc_u32 s1, s11, 0
	s_add_i32 s73, s39, 0x8000
	s_mov_b32 m0, s73
	s_nop 0
	global_load_lds_dwordx4 v157, s[0:1]
	s_add_i32 s76, s39, 0xa000
	v_lshlrev_b64 v[138:139], 9, v[130:131]
	v_add_u32_e32 v130, 0x80, v128
	s_mov_b32 m0, s76
	s_nop 0
	global_load_lds_dwordx4 v165, s[0:1]
	s_add_u32 s0, s52, 0x80080
	v_lshlrev_b64 v[140:141], 9, v[130:131]
	v_add_u32_e32 v130, 0x90, v128
	s_addc_u32 s1, s53, 0
	s_add_i32 s77, s39, 0x1c000
	s_mov_b32 m0, s77
	s_nop 0
	global_load_lds_dwordx4 v161, s[0:1]
	v_lshlrev_b64 v[142:143], 9, v[130:131]
	v_add_u32_e32 v130, 0xa0, v128
	s_add_i32 s78, s39, 0x1e000
	s_mov_b32 m0, s78
	s_nop 0
	global_load_lds_dwordx4 v169, s[0:1]
	v_lshlrev_b64 v[144:145], 9, v[130:131]
	v_add_u32_e32 v130, 0xb0, v128
	v_mov_b32_e32 v5, 0xcf
	v_lshlrev_b32_e32 v0, 3, v2
	s_cmp_eq_u64 s[18:19], 0
	s_cbranch_scc1 .Lstag_skip_13
	s_barrier
.Lstag_skip_13:
	s_waitcnt vmcnt(8)
	s_barrier
	s_waitcnt vmcnt(6)
	s_add_i32 s79, s39, 0xc000
	v_mov_b32_e32 v129, v131
	v_lshlrev_b64 v[146:147], 9, v[130:131]
	v_bitop3_b32 v1, s5, v5, v1 bitop3:0xc8
	v_lshlrev_b32_e32 v130, 5, v2
	s_cmpk_lt_u32 s4, 0x100
	v_lshlrev_b64 v[132:133], 9, v[128:129]
	v_lshl_add_u64 v[148:149], s[8:9], 0, v[130:131]
	v_lshl_add_u32 v129, v1, 2, s29
	v_add_u32_e32 v1, 0, v3
	v_lshlrev_b32_e32 v130, 1, v0
	v_mbcnt_lo_u32_b32 v0, -1, 0
	s_cselect_b64 s[24:25], -1, 0
	v_cmp_eq_u32_e64 s[6:7], 0, v2
	s_mov_b32 s21, s17
	s_add_i32 s80, s39, 0xe000
	s_ashr_i32 s81, s27, 31
	s_ashr_i32 s82, s2, 31
	v_mov_b64_e32 v[150:151], 0x800
	v_mov_b64_e32 v[152:153], 0x7ff
	v_add_u32_e32 v173, 0x10000, v1
	v_add_u32_e32 v177, 0x14000, v1
	v_add_u32_e32 v181, 0, v4
	v_add_u32_e32 v190, 0x18000, v1
	v_add_u32_e32 v191, 0x1c000, v1
	v_mov_b32_e32 v192, 0x358637bd
	s_mov_b32 s26, 0x3e6d3388
	s_mov_b32 s28, 0x3f07dc22
	s_mov_b32 s30, 0xbf3a00e3
	s_mov_b32 s34, 0x3f35f0e3
	s_mov_b32 s36, 0xbe11a98e
	s_mov_b32 s38, 0x3e027906
	s_mov_b32 s40, 0xbf38aa3b
	v_mbcnt_hi_u32_b32 v193, -1, v0
	s_mov_b32 s83, 0
	s_barrier
	s_branch .LBB0_625

; __device__ __forceinline__ unsigned xb_add(unsigned* p, unsigned v) { return __hip_atomic_fetch_add(p, v, __ATOMIC_RELAXED, __HIP_MEMORY_SCOPE_AGENT); }
; __device__ __forceinline__ void xcd_barrier(const XcdBarrier& b) {
;     ...
;     if (threadIdx.x == 0) {
;         unsigned* bar = b.bar;
;         __builtin_amdgcn_s_waitcnt(0);
;         unsigned nloc = b.st[0], nx = b.st[1];
;         if (nloc == 0u) { xcd_barrier_complete(bar, b.x, nloc, nx); b.st[0] = nloc; b.st[1] = nx; }
;         const unsigned old = xb_add(&bar[XB_XSUB(b.x)], 1u);
;         const unsigned gen = old / nloc;
;         if (old + 1u == (gen + 1u) * nloc) {
.LBB0_720:
	s_mov_b64 s[0:1], exec
	s_lshl_b32 s4, s3, 8
	v_mbcnt_lo_u32_b32 v1, s0, 0
	s_add_u32 s10, s74, s4
	v_mbcnt_hi_u32_b32 v1, s1, v1
	s_addc_u32 s11, s75, 0
	v_cmp_eq_u32_e32 vcc, 0, v1
	s_and_saveexec_b64 s[12:13], vcc
	s_cbranch_execz .LBB0_722
	s_bcnt1_i32_b64 s0, s[0:1]
	v_mov_b32_e32 v3, 0x1000
	v_mov_b32_e32 v4, s0
	global_atomic_add v3, v3, v4, s[10:11] offset:1024 sc0
	buffer_inv sc1

; __device__ __forceinline__ unsigned xb_ld(unsigned* p)              { return __hip_atomic_load(p, __ATOMIC_RELAXED, __HIP_MEMORY_SCOPE_AGENT); }
; __device__ __forceinline__ unsigned xb_add(unsigned* p, unsigned v) { return __hip_atomic_fetch_add(p, v, __ATOMIC_RELAXED, __HIP_MEMORY_SCOPE_AGENT); }
; #define XB_SPIN(cond, bar) do { unsigned _sp = 0; while (cond) { __builtin_amdgcn_s_sleep(1); \
;     if ((++_sp & 255u) == 0u) { if (xb_ld(&(bar)[XB_TMO])) break; if (_sp > XB_SPIN_CAP) { atomicAdd(&(bar)[XB_TMO], 1u); break; } } } } while (0)
; __device__ __forceinline__ void xcd_barrier(const XcdBarrier& b) {
;     ...
;         if (old + 1u == (gen + 1u) * nloc) {
;             __builtin_amdgcn_fence(__ATOMIC_RELEASE, "agent");
;             asm volatile("s_waitcnt vmcnt(0)" ::: "memory");
;             const unsigned og = xb_add(&bar[XB_TOP], 1u);
;             const unsigned tg = og / nx;
;             if (og + 1u == (tg + 1u) * nx) xb_add(&bar[XB_TOPGEN], 1u);
;             else XB_SPIN(xb_ld(&bar[XB_TOPGEN]) == tg, bar);
;             __builtin_amdgcn_fence(__ATOMIC_ACQUIRE, "agent");
;             xb_add(&bar[XB_XGEN(b.x)], 1u);
;             asm volatile("s_waitcnt vmcnt(0)" ::: "memory");
;         } else {
;             XB_SPIN(xb_ld(&bar[XB_XGEN(b.x)]) == gen, bar);
;             __builtin_amdgcn_fence(__ATOMIC_ACQUIRE, "agent");
;             asm volatile("s_waitcnt vmcnt(0)" ::: "memory");
;         }
.LBB0_732:
	s_or_b64 exec, exec, s[16:17]
	s_xor_b64 s[4:5], s[18:19], -1
	s_and_saveexec_b64 s[14:15], s[4:5]
	s_xor_b64 s[14:15], exec, s[14:15]
	s_cbranch_execz .LBB0_735
	s_mov_b64 s[14:15], exec
	v_mbcnt_lo_u32_b32 v0, s14, 0
	v_mbcnt_hi_u32_b32 v0, s15, v0
	v_cmp_eq_u32_e32 vcc, 0, v0
	s_and_b64 s[4:5], exec, vcc
	s_mov_b64 exec, s[4:5]
	s_cbranch_execz .LBB0_735
	s_bcnt1_i32_b64 s4, s[14:15]
	v_mov_b32_e32 v0, 0
	v_mov_b32_e32 v1, s4
	global_atomic_add v0, v1, s[74:75] offset:512
.LBB0_735:
	s_or_b64 exec, exec, s[0:1]
	s_waitcnt vmcnt(0)
	s_waitcnt vmcnt(0)
.LBB0_736:
	s_andn2_saveexec_b64 s[0:1], s[12:13]
	s_cbranch_execz .LBB0_756
	s_mov_b64 s[0:1], exec
	buffer_wbl2 sc1
	s_waitcnt lgkmcnt(0)
	s_waitcnt vmcnt(0)
	v_mbcnt_lo_u32_b32 v1, s0, 0
	v_mbcnt_hi_u32_b32 v1, s1, v1
	v_cmp_eq_u32_e32 vcc, 0, v1
	s_and_saveexec_b64 s[12:13], vcc
	s_cbranch_execz .LBB0_739
	s_bcnt1_i32_b64 s0, s[0:1]
	v_mov_b32_e32 v2, 0x3000
	v_mov_b32_e32 v3, s0
	global_atomic_add v2, v2, v3, s[74:75] offset:1024 sc0

; __device__ __forceinline__ unsigned xb_ld(unsigned* p)              { return __hip_atomic_load(p, __ATOMIC_RELAXED, __HIP_MEMORY_SCOPE_AGENT); }
; __device__ __forceinline__ unsigned xb_add(unsigned* p, unsigned v) { return __hip_atomic_fetch_add(p, v, __ATOMIC_RELAXED, __HIP_MEMORY_SCOPE_AGENT); }
; #define XB_SPIN(cond, bar) do { unsigned _sp = 0; while (cond) { __builtin_amdgcn_s_sleep(1); \
;     if ((++_sp & 255u) == 0u) { if (xb_ld(&(bar)[XB_TMO])) break; if (_sp > XB_SPIN_CAP) { atomicAdd(&(bar)[XB_TMO], 1u); break; } } } } while (0)
; __device__ __forceinline__ void xcd_barrier(const XcdBarrier& b) {
;     ...
;             const unsigned og = xb_add(&bar[XB_TOP], 1u);
;             const unsigned tg = og / nx;
;             if (og + 1u == (tg + 1u) * nx) xb_add(&bar[XB_TOPGEN], 1u);
;             else XB_SPIN(xb_ld(&bar[XB_TOPGEN]) == tg, bar);
;             __builtin_amdgcn_fence(__ATOMIC_ACQUIRE, "agent");
;             xb_add(&bar[XB_XGEN(b.x)], 1u);
;             asm volatile("s_waitcnt vmcnt(0)" ::: "memory");
.LBB0_753:
	s_or_b64 exec, exec, s[0:1]
	s_mov_b64 s[0:1], exec
	v_mbcnt_lo_u32_b32 v0, s0, 0
	v_mbcnt_hi_u32_b32 v0, s1, v0
	v_cmp_eq_u32_e32 vcc, 0, v0
	s_waitcnt vmcnt(0)
	s_and_saveexec_b64 s[12:13], vcc
	s_cbranch_execz .LBB0_755
	s_bcnt1_i32_b64 s0, s[0:1]
	v_mov_b32_e32 v0, 0x2000
	v_mov_b32_e32 v1, s0
	global_atomic_add v0, v1, s[10:11] offset:1024

; __device__ __forceinline__ unsigned xb_ld(unsigned* p)              { return __hip_atomic_load(p, __ATOMIC_RELAXED, __HIP_MEMORY_SCOPE_AGENT); }
; __device__ __forceinline__ unsigned xb_add(unsigned* p, unsigned v) { return __hip_atomic_fetch_add(p, v, __ATOMIC_RELAXED, __HIP_MEMORY_SCOPE_AGENT); }
; #define XB_SPIN(cond, bar) do { unsigned _sp = 0; while (cond) { __builtin_amdgcn_s_sleep(1); \
;     if ((++_sp & 255u) == 0u) { if (xb_ld(&(bar)[XB_TMO])) break; if (_sp > XB_SPIN_CAP) { atomicAdd(&(bar)[XB_TMO], 1u); break; } } } } while (0)
; __device__ __forceinline__ void xcd_barrier(const XcdBarrier& b) {
;     ...
;         if (old + 1u == (gen + 1u) * nloc) {
;             __builtin_amdgcn_fence(__ATOMIC_RELEASE, "agent");
;             asm volatile("s_waitcnt vmcnt(0)" ::: "memory");
;             const unsigned og = xb_add(&bar[XB_TOP], 1u);
;             const unsigned tg = og / nx;
;             if (og + 1u == (tg + 1u) * nx) xb_add(&bar[XB_TOPGEN], 1u);
;             else XB_SPIN(xb_ld(&bar[XB_TOPGEN]) == tg, bar);
;             __builtin_amdgcn_fence(__ATOMIC_ACQUIRE, "agent");
;             xb_add(&bar[XB_XGEN(b.x)], 1u);
;             asm volatile("s_waitcnt vmcnt(0)" ::: "memory");
;         } else {
;             XB_SPIN(xb_ld(&bar[XB_XGEN(b.x)]) == gen, bar);
;             __builtin_amdgcn_fence(__ATOMIC_ACQUIRE, "agent");
;             asm volatile("s_waitcnt vmcnt(0)" ::: "memory");
;         }
.LBB0_795:
	s_or_b64 exec, exec, s[16:17]
	s_xor_b64 s[4:5], s[18:19], -1
	s_and_saveexec_b64 s[14:15], s[4:5]
	s_xor_b64 s[14:15], exec, s[14:15]
	s_cbranch_execz .LBB0_798
	s_mov_b64 s[14:15], exec
	v_mbcnt_lo_u32_b32 v0, s14, 0
	v_mbcnt_hi_u32_b32 v0, s15, v0
	v_cmp_eq_u32_e32 vcc, 0, v0
	s_and_b64 s[4:5], exec, vcc
	s_mov_b64 exec, s[4:5]
	s_cbranch_execz .LBB0_798
	s_bcnt1_i32_b64 s4, s[14:15]
	v_mov_b32_e32 v0, 0
	v_mov_b32_e32 v1, s4
	global_atomic_add v0, v1, s[74:75] offset:512
.LBB0_798:
	s_or_b64 exec, exec, s[0:1]
	s_waitcnt vmcnt(0)
	s_waitcnt vmcnt(0)
.LBB0_799:
	s_andn2_saveexec_b64 s[0:1], s[12:13]
	s_cbranch_execz .LBB0_819
	s_mov_b64 s[0:1], exec
	buffer_wbl2 sc1
	s_waitcnt lgkmcnt(0)
	s_waitcnt vmcnt(0)
	v_mbcnt_lo_u32_b32 v1, s0, 0
	v_mbcnt_hi_u32_b32 v1, s1, v1
	v_cmp_eq_u32_e32 vcc, 0, v1
	s_and_saveexec_b64 s[12:13], vcc
	s_cbranch_execz .LBB0_802
	s_bcnt1_i32_b64 s0, s[0:1]
	v_mov_b32_e32 v2, 0x3000
	v_mov_b32_e32 v3, s0
	global_atomic_add v2, v2, v3, s[74:75] offset:1024 sc0

; #define PG8_STAGE(bufoff, gbase, voff) do { const unsigned long long gb_ = (unsigned long long)(gbase); _Pragma("unroll") for (int _i = 0; _i < 2; ++_i) { unsigned keep_; \
;         asm volatile("s_mov_b32 m0, %2\n\ts_nop 0\n\tglobal_load_lds_dwordx4 %0, %1" : : "v"((voff)[_i]), "s"(gb_), "s"((unsigned)(size_t)(lds + (bufoff) + ldsw + _i * 8192)) : "memory", "m0"); (void)keep_; } } while (0)
; #define PG8_WAIT_V(n) asm volatile("s_waitcnt vmcnt(" #n ")" ::: "memory")
; #define PG8_BAR __builtin_amdgcn_s_barrier()
; template <class Epi, class Sched, bool ALIGN_EPI = false, bool SP2 = false>
; __device__ __forceinline__ void gemm_phase(PG8_LAS unsigned char* lds, const Gemm g, const Sched& S, const Epi& E) {
;     ...
;     const unsigned ldsw = (unsigned)wid * 1024u;
;     const int aoff = lds_byte(wr * 64 + fr, fq * 8), boff = lds_byte(wc * 32 + fr, fq * 8);
;     ...
;     if constexpr (SP2) {
;         PG8_STAGE(PG8_SB(0, 0), cB, voffB); PG8_STAGE(PG8_SB(0, 1), cB + hstepB, voffB); PG8_STAGE(PG8_SA(0, 0), cA, voffA); PG8_STAGE(PG8_SA(0, 1), cA + hstepA, voffA);
;         if (wr == 1) PG8_BAR;
;         PG8_WAIT_V(2); PG8_BAR;
;         PG8_STAGE(PG8_SB(1, 0), cB + kstep, voffB); PG8_STAGE(PG8_SA(1, 0), cA + kstep, voffA); PG8_STAGE(PG8_SB(1, 1), cB + hstepB + kstep, voffB);
;         PG8_WAIT_V(6); PG8_BAR;
.LBB0_830:
	s_add_u32 s16, s74, 0x6000000
	s_addc_u32 s17, s75, 0
	s_add_u32 s18, s74, 0x2000000
	s_addc_u32 s19, s75, 0
	v_bfe_u32 v0, v200, 4, 2
	s_add_u32 s20, s74, 0x200000
	v_and_b32_e32 v1, 15, v200
	v_lshlrev_b32_e32 v3, 4, v0
	v_lshlrev_b32_e32 v4, 2, v200
	s_addc_u32 s21, s75, 0
	s_and_b32 s59, s0, 3
	v_lshl_or_b32 v184, s1, 6, v1
	v_lshl_or_b32 v1, v1, 6, v3
	s_lshl_b32 s0, s1, 13
	v_and_b32_e32 v4, 32, v4
	v_bitop3_b32 v5, v1, s0, v4 bitop3:0xde
	v_lshlrev_b32_e32 v1, 6, v200
	s_movk_i32 s0, 0x3c0
	v_and_or_b32 v1, v1, s0, v3
	s_lshl_b32 s0, s59, 12
	v_mov_b32_e32 v185, 0
	v_lshlrev_b32_e32 v2, 3, v0
	v_bitop3_b32 v3, s0, v1, v4 bitop3:0xf6
	s_add_u32 s0, s38, 0x80
	v_cmp_eq_u32_e64 s[6:7], 0, v0
	v_or_b32_e32 v0, 16, v184
	v_mov_b32_e32 v1, v185
	s_addc_u32 s1, s39, 0
	s_add_i32 s60, s35, 0x18000
	s_mov_b32 m0, s60
	s_nop 0
	global_load_lds_dwordx4 v201, s[0:1]
	s_add_i32 s61, s35, 0x1a000
	v_lshlrev_b64 v[190:191], 9, v[0:1]
	v_or_b32_e32 v0, 32, v184
	s_mov_b32 m0, s61
	s_nop 0
	global_load_lds_dwordx4 v213, s[0:1]
	s_add_u32 s0, s40, 0x80
	v_lshlrev_b64 v[192:193], 9, v[0:1]
	v_or_b32_e32 v0, 48, v184
	s_addc_u32 s1, s41, 0
	s_add_i32 s62, s35, 0x8000
	s_mov_b32 m0, s62
	s_nop 0
	global_load_lds_dwordx4 v187, s[0:1]
	s_add_i32 s63, s35, 0xa000
	v_lshlrev_b64 v[194:195], 9, v[0:1]
	v_add_u32_e32 v0, 0x80, v184
	s_mov_b32 m0, s63
	s_nop 0
	global_load_lds_dwordx4 v212, s[0:1]
	s_add_u32 s0, s38, 0x100080
	v_lshlrev_b64 v[196:197], 9, v[0:1]
	v_add_u32_e32 v0, 0x90, v184
	s_addc_u32 s1, s39, 0
	s_add_i32 s64, s35, 0x1c000
	s_mov_b32 m0, s64
	s_nop 0
	global_load_lds_dwordx4 v201, s[0:1]
	v_lshlrev_b64 v[198:199], 9, v[0:1]
	v_add_u32_e32 v0, 0xa0, v184
	s_add_i32 s65, s35, 0x1e000
	s_mov_b32 m0, s65
	s_nop 0
	global_load_lds_dwordx4 v213, s[0:1]
	v_lshlrev_b64 v[202:203], 9, v[0:1]
	v_add_u32_e32 v0, 0xb0, v184
	s_cmp_eq_u64 s[14:15], 0
	s_cbranch_scc1 .Lstag_skip_12
	s_barrier
.Lstag_skip_12:
	s_waitcnt vmcnt(8)
	s_barrier
	s_waitcnt vmcnt(6)
	s_add_i32 s66, s35, 0xc000
	v_lshlrev_b64 v[204:205], 9, v[0:1]
	v_add_u32_e32 v0, 0, v3
	s_cmpk_lt_u32 s8, 0x100
	v_lshlrev_b64 v[188:189], 9, v[184:185]
	v_add_u32_e32 v185, 0x10000, v0
	v_add_u32_e32 v214, 0x14000, v0
	v_add_u32_e32 v216, 0x18000, v0
	v_add_u32_e32 v217, 0x1c000, v0
	v_mbcnt_lo_u32_b32 v0, -1, 0
	s_cselect_b64 s[22:23], -1, 0
	v_lshl_or_b32 v186, s59, 5, v2
	s_add_i32 s67, s35, 0xe000
	s_waitcnt lgkmcnt(0)
	s_ashr_i32 s68, s4, 31
	s_ashr_i32 s69, s2, 31
	v_mov_b64_e32 v[206:207], 0x200
	v_mov_b64_e32 v[208:209], 0x1ff
	v_add_u32_e32 v215, 0, v5
	v_mbcnt_hi_u32_b32 v218, -1, v0
	s_mov_b32 s70, 0
	s_barrier
	s_branch .LBB0_833

; __device__ __forceinline__ unsigned xb_ld(unsigned* p)              { return __hip_atomic_load(p, __ATOMIC_RELAXED, __HIP_MEMORY_SCOPE_AGENT); }
; __device__ __forceinline__ unsigned xb_add(unsigned* p, unsigned v) { return __hip_atomic_fetch_add(p, v, __ATOMIC_RELAXED, __HIP_MEMORY_SCOPE_AGENT); }
; #define XB_SPIN(cond, bar) do { unsigned _sp = 0; while (cond) { __builtin_amdgcn_s_sleep(1); \
;     if ((++_sp & 255u) == 0u) { if (xb_ld(&(bar)[XB_TMO])) break; if (_sp > XB_SPIN_CAP) { atomicAdd(&(bar)[XB_TMO], 1u); break; } } } } while (0)
; __device__ __forceinline__ void xcd_barrier(const XcdBarrier& b) {
;     ...
;         if (old + 1u == (gen + 1u) * nloc) {
;             __builtin_amdgcn_fence(__ATOMIC_RELEASE, "agent");
;             asm volatile("s_waitcnt vmcnt(0)" ::: "memory");
;             const unsigned og = xb_add(&bar[XB_TOP], 1u);
;             const unsigned tg = og / nx;
;             if (og + 1u == (tg + 1u) * nx) xb_add(&bar[XB_TOPGEN], 1u);
;             else XB_SPIN(xb_ld(&bar[XB_TOPGEN]) == tg, bar);
;             __builtin_amdgcn_fence(__ATOMIC_ACQUIRE, "agent");
;             xb_add(&bar[XB_XGEN(b.x)], 1u);
;             asm volatile("s_waitcnt vmcnt(0)" ::: "memory");
;         } else {
;             XB_SPIN(xb_ld(&bar[XB_XGEN(b.x)]) == gen, bar);
;             __builtin_amdgcn_fence(__ATOMIC_ACQUIRE, "agent");
;             asm volatile("s_waitcnt vmcnt(0)" ::: "memory");
;         }
.LBB0_893:
	s_or_b64 exec, exec, s[18:19]
	s_xor_b64 s[4:5], s[20:21], -1
	s_and_saveexec_b64 s[16:17], s[4:5]
	s_xor_b64 s[16:17], exec, s[16:17]
	s_cbranch_execz .LBB0_896
	s_mov_b64 s[16:17], exec
	v_mbcnt_lo_u32_b32 v0, s16, 0
	v_mbcnt_hi_u32_b32 v0, s17, v0
	v_cmp_eq_u32_e32 vcc, 0, v0
	s_and_b64 s[4:5], exec, vcc
	s_mov_b64 exec, s[4:5]
	s_cbranch_execz .LBB0_896
	s_bcnt1_i32_b64 s4, s[16:17]
	v_mov_b32_e32 v0, 0
	v_mov_b32_e32 v1, s4
	global_atomic_add v0, v1, s[74:75] offset:512
.LBB0_896:
	s_or_b64 exec, exec, s[0:1]
	s_waitcnt vmcnt(0)
	s_waitcnt vmcnt(0)
.LBB0_897:
	s_andn2_saveexec_b64 s[0:1], s[14:15]
	s_cbranch_execz .LBB0_917
	s_mov_b64 s[0:1], exec
	buffer_wbl2 sc1
	s_waitcnt lgkmcnt(0)
	s_waitcnt vmcnt(0)
	v_mbcnt_lo_u32_b32 v1, s0, 0
	v_mbcnt_hi_u32_b32 v1, s1, v1
	v_cmp_eq_u32_e32 vcc, 0, v1
	s_and_saveexec_b64 s[14:15], vcc
	s_cbranch_execz .LBB0_900
	s_bcnt1_i32_b64 s0, s[0:1]
	v_mov_b32_e32 v2, 0x3000
	v_mov_b32_e32 v3, s0
	global_atomic_add v2, v2, v3, s[74:75] offset:1024 sc0

; #define PG8_STAGE(bufoff, gbase, voff) do { const unsigned long long gb_ = (unsigned long long)(gbase); _Pragma("unroll") for (int _i = 0; _i < 2; ++_i) { unsigned keep_; \
;         asm volatile("s_mov_b32 m0, %2\n\ts_nop 0\n\tglobal_load_lds_dwordx4 %0, %1" : : "v"((voff)[_i]), "s"(gb_), "s"((unsigned)(size_t)(lds + (bufoff) + ldsw + _i * 8192)) : "memory", "m0"); (void)keep_; } } while (0)
; #define PG8_WAIT_V(n) asm volatile("s_waitcnt vmcnt(" #n ")" ::: "memory")
; #define PG8_BAR __builtin_amdgcn_s_barrier()
; template <class Epi, class Sched, bool ALIGN_EPI = false, bool SP2 = false>
; __device__ __forceinline__ void gemm_phase(PG8_LAS unsigned char* lds, const Gemm g, const Sched& S, const Epi& E) {
;     ...
;     const unsigned ldsw = (unsigned)wid * 1024u;
;     const int aoff = lds_byte(wr * 64 + fr, fq * 8), boff = lds_byte(wc * 32 + fr, fq * 8);
;     ...
;     if constexpr (SP2) {
;         PG8_STAGE(PG8_SB(0, 0), cB, voffB); PG8_STAGE(PG8_SB(0, 1), cB + hstepB, voffB); PG8_STAGE(PG8_SA(0, 0), cA, voffA); PG8_STAGE(PG8_SA(0, 1), cA + hstepA, voffA);
;         if (wr == 1) PG8_BAR;
;         PG8_WAIT_V(2); PG8_BAR;
;         PG8_STAGE(PG8_SB(1, 0), cB + kstep, voffB); PG8_STAGE(PG8_SA(1, 0), cA + kstep, voffA); PG8_STAGE(PG8_SB(1, 1), cB + hstepB + kstep, voffB);
;         PG8_WAIT_V(6); PG8_BAR;
.LBB0_947:
	v_lshlrev_b32_e32 v1, 2, v129
	s_lshl_b32 s20, s0, 6
	v_lshl_or_b32 v0, v129, 6, v165
	s_lshl_b32 s0, s0, 13
	v_and_b32_e32 v1, 32, v1
	v_bitop3_b32 v0, v0, s0, v1 bitop3:0xde
	s_lshl_b32 s0, s1, 5
	s_and_b32 s21, s0, 0x60
	s_add_u32 s52, s74, 0xe000000
	s_addc_u32 s53, s75, 0
	s_mov_b32 s22, 0x160000
	s_and_b64 s[0:1], s[18:19], exec
	v_or_b32_e32 v130, s20, v129
	s_cselect_b32 s54, s22, 0x200000
	s_add_u32 s0, s34, 0x80
	s_addc_u32 s1, s35, 0
	s_add_i32 s55, s31, 0x18000
	s_mov_b32 m0, s55
	s_nop 0
	global_load_lds_dwordx4 v175, s[0:1]
	s_add_i32 s56, s31, 0x1a000
	v_mov_b32_e32 v133, 0
	v_or_b32_e32 v132, 16, v130
	s_mov_b32 m0, s56
	s_nop 0
	global_load_lds_dwordx4 v176, s[0:1]
	s_add_u32 s0, s8, 0x80
	v_lshlrev_b64 v[136:137], 8, v[132:133]
	v_or_b32_e32 v132, 32, v130
	s_addc_u32 s1, s9, 0
	s_add_i32 s57, s31, 0x8000
	s_mov_b32 m0, s57
	s_nop 0
	global_load_lds_dwordx4 v161, s[0:1]
	s_add_i32 s58, s31, 0xa000
	v_lshlrev_b64 v[138:139], 8, v[132:133]
	v_or_b32_e32 v132, 48, v130
	s_mov_b32 m0, s58
	s_nop 0
	global_load_lds_dwordx4 v163, s[0:1]
	s_add_u32 s0, s34, 0x80080
	v_lshlrev_b64 v[140:141], 8, v[132:133]
	v_add_u32_e32 v132, 0x80, v130
	s_addc_u32 s1, s35, 0
	s_add_i32 s59, s31, 0x1c000
	s_mov_b32 m0, s59
	s_nop 0
	global_load_lds_dwordx4 v175, s[0:1]
	v_lshlrev_b64 v[142:143], 8, v[132:133]
	v_add_u32_e32 v132, 0x90, v130
	s_add_i32 s60, s31, 0x1e000
	s_mov_b32 m0, s60
	s_nop 0
	global_load_lds_dwordx4 v176, s[0:1]
	v_lshlrev_b64 v[144:145], 8, v[132:133]
	v_add_u32_e32 v132, 0xa0, v130
	v_lshl_or_b32 v1, s21, 7, v167
	s_cmp_eq_u64 s[16:17], 0
	s_cbranch_scc1 .Lstag_skip_11
	s_barrier
.Lstag_skip_11:
	s_waitcnt vmcnt(8)
	s_barrier
	s_waitcnt vmcnt(6)
	s_add_i32 s61, s31, 0xc000
	v_mov_b32_e32 v2, 0xcf
	v_lshlrev_b64 v[146:147], 8, v[132:133]
	v_add_u32_e32 v132, 0xb0, v130
	s_cmpk_lt_u32 s14, 0x100
	v_bitop3_b32 v2, s20, v2, v129 bitop3:0xc8
	v_mov_b32_e32 v131, v133
	v_lshlrev_b64 v[148:149], 8, v[132:133]
	v_lshlrev_b32_e32 v132, 2, v128
	v_add_u32_e32 v1, 0, v1
	v_add_u32_e32 v179, 0, v0
	v_mbcnt_lo_u32_b32 v0, -1, 0
	s_cselect_b64 s[18:19], -1, 0
	v_lshlrev_b64 v[134:135], 8, v[130:131]
	s_add_i32 s62, s31, 0xe000
	s_ashr_i32 s63, s33, 31
	s_ashr_i32 s64, s2, 31
	v_lshl_add_u64 v[150:151], s[6:7], 0, v[132:133]
	v_lshl_add_u32 v131, v2, 2, s4
	v_mov_b64_e32 v[152:153], 0xb00
	v_mov_b64_e32 v[154:155], 0xaff
	s_movk_i32 s65, 0x161
	v_add_u32_e32 v177, 0x10000, v1
	v_add_u32_e32 v178, 0x14000, v1
	v_add_u32_e32 v180, 0x18000, v1
	v_add_u32_e32 v181, 0x1c000, v1
	v_mov_b32_e32 v182, 0x358637bd
	s_lshl_b32 s14, s21, 1
	v_lshlrev_b32_e32 v132, 1, v128
	v_mbcnt_hi_u32_b32 v183, -1, v0
	s_mov_b32 s66, s15
	s_barrier
	s_branch .LBB0_950

; #define PG8_STAGE(bufoff, gbase, voff) do { const unsigned long long gb_ = (unsigned long long)(gbase); _Pragma("unroll") for (int _i = 0; _i < 2; ++_i) { unsigned keep_; \
;         asm volatile("s_mov_b32 m0, %2\n\ts_nop 0\n\tglobal_load_lds_dwordx4 %0, %1" : : "v"((voff)[_i]), "s"(gb_), "s"((unsigned)(size_t)(lds + (bufoff) + ldsw + _i * 8192)) : "memory", "m0"); (void)keep_; } } while (0)
; #define PG8_WAIT_V(n) asm volatile("s_waitcnt vmcnt(" #n ")" ::: "memory")
; #define PG8_BAR __builtin_amdgcn_s_barrier()
; template <class Epi, class Sched, bool ALIGN_EPI = false, bool SP2 = false>
; __device__ __forceinline__ void gemm_phase(PG8_LAS unsigned char* lds, const Gemm g, const Sched& S, const Epi& E) {
;     ...
;     if constexpr (SP2) {
;         PG8_STAGE(PG8_SB(0, 0), cB, voffB); PG8_STAGE(PG8_SB(0, 1), cB + hstepB, voffB); PG8_STAGE(PG8_SA(0, 0), cA, voffA); PG8_STAGE(PG8_SA(0, 1), cA + hstepA, voffA);
;         if (wr == 1) PG8_BAR;
;         PG8_WAIT_V(2); PG8_BAR;
;         PG8_STAGE(PG8_SB(1, 0), cB + kstep, voffB); PG8_STAGE(PG8_SA(1, 0), cA + kstep, voffA); PG8_STAGE(PG8_SB(1, 1), cB + hstepB + kstep, voffB);
;         PG8_WAIT_V(6); PG8_BAR;
.LBB0_999:
	s_add_u32 s12, s74, 0xa000000
	v_lshlrev_b32_e32 v1, 2, v129
	s_sext_i32_i8 s84, s0
	s_addc_u32 s13, s75, 0
	v_lshl_or_b32 v0, v129, 6, v165
	s_lshl_b32 s0, s7, 13
	v_and_b32_e32 v1, 32, v1
	v_bitop3_b32 v0, v0, s0, v1 bitop3:0xde
	s_lshl_b32 s0, s1, 5
	v_lshl_or_b32 v134, s7, 6, v129
	s_and_b32 s7, s0, 0x60
	s_add_u32 s0, s36, 0x80
	s_addc_u32 s1, s37, 0
	s_add_i32 s69, s61, 0x18000
	s_mov_b32 m0, s69
	s_nop 0
	global_load_lds_dwordx4 v132, s[0:1]
	s_add_i32 s70, s61, 0x1a000
	s_mov_b32 m0, s70
	s_nop 0
	global_load_lds_dwordx4 v133, s[0:1]
	s_add_u32 s0, s38, 0x80
	s_addc_u32 s1, s39, 0
	s_add_i32 s71, s61, 0x8000
	s_mov_b32 m0, s71
	s_nop 0
	global_load_lds_dwordx4 v161, s[0:1]
	s_add_i32 s72, s61, 0xa000
	s_mov_b32 m0, s72
	s_nop 0
	global_load_lds_dwordx4 v163, s[0:1]
	s_add_u32 s0, s36, 0x10080
	s_addc_u32 s1, s37, 0
	s_add_i32 s73, s61, 0x1c000
	s_mov_b32 m0, s73
	s_nop 0
	global_load_lds_dwordx4 v132, s[0:1]
	s_add_i32 s76, s61, 0x1e000
	s_mov_b32 m0, s76
	s_nop 0
	global_load_lds_dwordx4 v133, s[0:1]
	v_lshl_or_b32 v1, s7, 7, v167
	s_cmp_eq_u64 s[8:9], 0
	s_cbranch_scc1 .Lstag_skip_10
	s_barrier
.Lstag_skip_10:
	s_waitcnt vmcnt(8)
	s_barrier
	s_waitcnt vmcnt(6)
	s_add_i32 s77, s61, 0xc000
	s_cmpk_lt_u32 s6, 0x100
	v_add_u32_e32 v1, 0, v1
	s_cselect_b64 s[14:15], -1, 0
	s_add_i32 s78, s61, 0xe000
	s_ashr_i32 s79, s33, 31
	v_or_b32_e32 v135, s7, v128
	v_mov_b64_e32 v[128:129], 0x200
	v_mov_b64_e32 v[130:131], 0x1ff
	v_add_u32_e32 v136, 0x10000, v1
	v_add_u32_e32 v137, 0x14000, v1
	v_add_u32_e32 v138, 0, v0
	v_add_u32_e32 v139, 0x18000, v1
	v_add_u32_e32 v140, 0x1c000, v1
	s_mov_b64 s[16:17], 0x80000
	s_mov_b32 s80, 0x80000
	s_mov_b64 s[18:19], 0x90000
	s_mov_b32 s81, 0x90000
	s_mov_b64 s[20:21], 0xa0000
	s_mov_b32 s82, 0xa0000
	s_mov_b64 s[22:23], 0xb0000
	s_mov_b32 s83, 0xb0000
	s_barrier
	s_waitcnt vmcnt(0)
	s_branch .LBB0_1002

; __device__ __forceinline__ unsigned xb_ld(unsigned* p)              { return __hip_atomic_load(p, __ATOMIC_RELAXED, __HIP_MEMORY_SCOPE_AGENT); }
; __device__ __forceinline__ unsigned xb_add(unsigned* p, unsigned v) { return __hip_atomic_fetch_add(p, v, __ATOMIC_RELAXED, __HIP_MEMORY_SCOPE_AGENT); }
; #define XB_SPIN(cond, bar) do { unsigned _sp = 0; while (cond) { __builtin_amdgcn_s_sleep(1); \
;     if ((++_sp & 255u) == 0u) { if (xb_ld(&(bar)[XB_TMO])) break; if (_sp > XB_SPIN_CAP) { atomicAdd(&(bar)[XB_TMO], 1u); break; } } } } while (0)
; __device__ __forceinline__ void xcd_barrier(const XcdBarrier& b) {
;     ...
;         if (old + 1u == (gen + 1u) * nloc) {
;             __builtin_amdgcn_fence(__ATOMIC_RELEASE, "agent");
;             asm volatile("s_waitcnt vmcnt(0)" ::: "memory");
;             const unsigned og = xb_add(&bar[XB_TOP], 1u);
;             const unsigned tg = og / nx;
;             if (og + 1u == (tg + 1u) * nx) xb_add(&bar[XB_TOPGEN], 1u);
;             else XB_SPIN(xb_ld(&bar[XB_TOPGEN]) == tg, bar);
;             __builtin_amdgcn_fence(__ATOMIC_ACQUIRE, "agent");
;             xb_add(&bar[XB_XGEN(b.x)], 1u);
;             asm volatile("s_waitcnt vmcnt(0)" ::: "memory");
;         } else {
;             XB_SPIN(xb_ld(&bar[XB_XGEN(b.x)]) == gen, bar);
;             __builtin_amdgcn_fence(__ATOMIC_ACQUIRE, "agent");
;             asm volatile("s_waitcnt vmcnt(0)" ::: "memory");
;         }
.LBB0_1046:
	s_or_b64 exec, exec, s[18:19]
	s_xor_b64 s[4:5], s[20:21], -1
	s_and_saveexec_b64 s[16:17], s[4:5]
	s_xor_b64 s[16:17], exec, s[16:17]
	s_cbranch_execz .LBB0_1049
	s_mov_b64 s[16:17], exec
	v_mbcnt_lo_u32_b32 v0, s16, 0
	v_mbcnt_hi_u32_b32 v0, s17, v0
	v_cmp_eq_u32_e32 vcc, 0, v0
	s_and_b64 s[4:5], exec, vcc
	s_mov_b64 exec, s[4:5]
	s_cbranch_execz .LBB0_1049
	s_bcnt1_i32_b64 s4, s[16:17]
	v_mov_b32_e32 v0, 0
	v_mov_b32_e32 v1, s4
	global_atomic_add v0, v1, s[74:75] offset:512
.LBB0_1049:
	s_or_b64 exec, exec, s[0:1]
	s_waitcnt vmcnt(0)
	s_waitcnt vmcnt(0)
.LBB0_1050:
	s_andn2_saveexec_b64 s[0:1], s[14:15]
	s_cbranch_execz .LBB0_1070
	s_mov_b64 s[0:1], exec
	buffer_wbl2 sc1
	s_waitcnt lgkmcnt(0)
	s_waitcnt vmcnt(0)
	v_mbcnt_lo_u32_b32 v1, s0, 0
	v_mbcnt_hi_u32_b32 v1, s1, v1
	v_cmp_eq_u32_e32 vcc, 0, v1
	s_and_saveexec_b64 s[14:15], vcc
	s_cbranch_execz .LBB0_1053
	s_bcnt1_i32_b64 s0, s[0:1]
	v_mov_b32_e32 v2, 0x3000
	v_mov_b32_e32 v3, s0
	global_atomic_add v2, v2, v3, s[74:75] offset:1024 sc0

; #define PG8_STAGE(bufoff, gbase, voff) do { const unsigned long long gb_ = (unsigned long long)(gbase); _Pragma("unroll") for (int _i = 0; _i < 2; ++_i) { unsigned keep_; \
;         asm volatile("s_mov_b32 m0, %2\n\ts_nop 0\n\tglobal_load_lds_dwordx4 %0, %1" : : "v"((voff)[_i]), "s"(gb_), "s"((unsigned)(size_t)(lds + (bufoff) + ldsw + _i * 8192)) : "memory", "m0"); (void)keep_; } } while (0)
; #define PG8_WAIT_V(n) asm volatile("s_waitcnt vmcnt(" #n ")" ::: "memory")
; #define PG8_BAR __builtin_amdgcn_s_barrier()
; template <class Epi, class Sched, bool ALIGN_EPI = false, bool SP2 = false>
; __device__ __forceinline__ void gemm_phase(PG8_LAS unsigned char* lds, const Gemm g, const Sched& S, const Epi& E) {
;     ...
;     const unsigned ldsw = (unsigned)wid * 1024u;
;     const int aoff = lds_byte(wr * 64 + fr, fq * 8), boff = lds_byte(wc * 32 + fr, fq * 8);
;     ...
;     if constexpr (SP2) {
;         PG8_STAGE(PG8_SB(0, 0), cB, voffB); PG8_STAGE(PG8_SB(0, 1), cB + hstepB, voffB); PG8_STAGE(PG8_SA(0, 0), cA, voffA); PG8_STAGE(PG8_SA(0, 1), cA + hstepA, voffA);
;         if (wr == 1) PG8_BAR;
;         PG8_WAIT_V(2); PG8_BAR;
;         PG8_STAGE(PG8_SB(1, 0), cB + kstep, voffB); PG8_STAGE(PG8_SA(1, 0), cA + kstep, voffA); PG8_STAGE(PG8_SB(1, 1), cB + hstepB + kstep, voffB);
;         PG8_WAIT_V(6); PG8_BAR;
.LBB0_1100:
	s_add_u32 s18, s74, 0x2000000
	s_addc_u32 s19, s75, 0
	s_add_u32 s20, s74, 0x6000000
	s_addc_u32 s21, s75, 0
	v_bfe_u32 v0, v200, 4, 2
	s_add_u32 s22, s74, 0x400000
	v_and_b32_e32 v1, 15, v200
	v_lshlrev_b32_e32 v3, 4, v0
	v_lshlrev_b32_e32 v4, 2, v200
	s_addc_u32 s23, s75, 0
	s_and_b32 s49, s0, 3
	v_lshl_or_b32 v184, s1, 6, v1
	v_lshl_or_b32 v1, v1, 6, v3
	s_lshl_b32 s0, s1, 13
	v_and_b32_e32 v4, 32, v4
	v_bitop3_b32 v5, v1, s0, v4 bitop3:0xde
	v_lshlrev_b32_e32 v1, 6, v200
	s_movk_i32 s0, 0x3c0
	v_and_or_b32 v1, v1, s0, v3
	s_lshl_b32 s0, s49, 12
	v_mov_b32_e32 v185, 0
	v_lshlrev_b32_e32 v2, 3, v0
	v_bitop3_b32 v3, s0, v1, v4 bitop3:0xf6
	s_add_u32 s0, s30, 0x80
	v_cmp_eq_u32_e64 s[6:7], 0, v0
	v_or_b32_e32 v0, 16, v184
	v_mov_b32_e32 v1, v185
	s_addc_u32 s1, s31, 0
	s_add_i32 s50, s41, 0x18000
	s_mov_b32 m0, s50
	s_nop 0
	global_load_lds_dwordx4 v201, s[0:1]
	s_add_i32 s51, s41, 0x1a000
	v_lshlrev_b64 v[190:191], 9, v[0:1]
	v_or_b32_e32 v0, 32, v184
	s_mov_b32 m0, s51
	s_nop 0
	global_load_lds_dwordx4 v213, s[0:1]
	s_add_u32 s0, s34, 0x80
	v_lshlrev_b64 v[192:193], 9, v[0:1]
	v_or_b32_e32 v0, 48, v184
	s_addc_u32 s1, s35, 0
	s_add_i32 s52, s41, 0x8000
	s_mov_b32 m0, s52
	s_nop 0
	global_load_lds_dwordx4 v187, s[0:1]
	s_add_i32 s53, s41, 0xa000
	v_lshlrev_b64 v[194:195], 9, v[0:1]
	v_add_u32_e32 v0, 0x80, v184
	s_mov_b32 m0, s53
	s_nop 0
	global_load_lds_dwordx4 v212, s[0:1]
	s_add_u32 s0, s30, 0x160080
	v_lshlrev_b64 v[196:197], 9, v[0:1]
	v_add_u32_e32 v0, 0x90, v184
	s_addc_u32 s1, s31, 0
	s_add_i32 s54, s41, 0x1c000
	s_mov_b32 m0, s54
	s_nop 0
	global_load_lds_dwordx4 v201, s[0:1]
	v_lshlrev_b64 v[198:199], 9, v[0:1]
	v_add_u32_e32 v0, 0xa0, v184
	s_add_i32 s55, s41, 0x1e000
	s_mov_b32 m0, s55
	s_nop 0
	global_load_lds_dwordx4 v213, s[0:1]
	v_lshlrev_b64 v[202:203], 9, v[0:1]
	v_add_u32_e32 v0, 0xb0, v184
	s_cmp_eq_u64 s[16:17], 0
	s_cbranch_scc1 .Lstag_skip_9
	s_barrier
.Lstag_skip_9:
	s_waitcnt vmcnt(8)
	s_barrier
	s_waitcnt vmcnt(6)
	s_add_i32 s56, s41, 0xc000
	v_lshlrev_b64 v[204:205], 9, v[0:1]
	v_add_u32_e32 v0, 0, v3
	s_cmpk_lt_u32 s8, 0x100
	v_lshlrev_b64 v[188:189], 9, v[184:185]
	v_add_u32_e32 v185, 0x10000, v0
	v_add_u32_e32 v214, 0x14000, v0
	v_add_u32_e32 v216, 0x18000, v0
	v_add_u32_e32 v217, 0x1c000, v0
	v_mbcnt_lo_u32_b32 v0, -1, 0
	s_cselect_b64 s[24:25], -1, 0
	v_lshl_or_b32 v186, s49, 5, v2
	s_add_i32 s57, s41, 0xe000
	s_ashr_i32 s58, s4, 31
	s_ashr_i32 s59, s2, 31
	v_mov_b64_e32 v[206:207], 0x200
	v_mov_b64_e32 v[208:209], 0x1ff
	v_add_u32_e32 v215, 0, v5
	v_mbcnt_hi_u32_b32 v218, -1, v0
	s_mov_b32 s60, 0
	s_barrier
	s_branch .LBB0_1103

; __device__ __forceinline__ unsigned xb_ld(unsigned* p)              { return __hip_atomic_load(p, __ATOMIC_RELAXED, __HIP_MEMORY_SCOPE_AGENT); }
; __device__ __forceinline__ unsigned xb_add(unsigned* p, unsigned v) { return __hip_atomic_fetch_add(p, v, __ATOMIC_RELAXED, __HIP_MEMORY_SCOPE_AGENT); }
; #define XB_SPIN(cond, bar) do { unsigned _sp = 0; while (cond) { __builtin_amdgcn_s_sleep(1); \
;     if ((++_sp & 255u) == 0u) { if (xb_ld(&(bar)[XB_TMO])) break; if (_sp > XB_SPIN_CAP) { atomicAdd(&(bar)[XB_TMO], 1u); break; } } } } while (0)
; __device__ __forceinline__ void xcd_barrier(const XcdBarrier& b) {
;     ...
;         if (old + 1u == (gen + 1u) * nloc) {
;             __builtin_amdgcn_fence(__ATOMIC_RELEASE, "agent");
;             asm volatile("s_waitcnt vmcnt(0)" ::: "memory");
;             const unsigned og = xb_add(&bar[XB_TOP], 1u);
;             const unsigned tg = og / nx;
;             if (og + 1u == (tg + 1u) * nx) xb_add(&bar[XB_TOPGEN], 1u);
;             else XB_SPIN(xb_ld(&bar[XB_TOPGEN]) == tg, bar);
;             __builtin_amdgcn_fence(__ATOMIC_ACQUIRE, "agent");
;             xb_add(&bar[XB_XGEN(b.x)], 1u);
;             asm volatile("s_waitcnt vmcnt(0)" ::: "memory");
;         } else {
;             XB_SPIN(xb_ld(&bar[XB_XGEN(b.x)]) == gen, bar);
;             __builtin_amdgcn_fence(__ATOMIC_ACQUIRE, "agent");
;             asm volatile("s_waitcnt vmcnt(0)" ::: "memory");
;         }
.LBB0_1167:
	s_or_b64 exec, exec, s[18:19]
	s_xor_b64 s[4:5], s[20:21], -1
	s_and_saveexec_b64 s[16:17], s[4:5]
	s_xor_b64 s[16:17], exec, s[16:17]
	s_cbranch_execz .LBB0_1170
	s_mov_b64 s[16:17], exec
	v_mbcnt_lo_u32_b32 v0, s16, 0
	v_mbcnt_hi_u32_b32 v0, s17, v0
	v_cmp_eq_u32_e32 vcc, 0, v0
	s_and_b64 s[4:5], exec, vcc
	s_mov_b64 exec, s[4:5]
	s_cbranch_execz .LBB0_1170
	s_bcnt1_i32_b64 s4, s[16:17]
	v_mov_b32_e32 v0, 0
	v_mov_b32_e32 v1, s4
	global_atomic_add v0, v1, s[74:75] offset:512
.LBB0_1170:
	s_or_b64 exec, exec, s[0:1]
	s_waitcnt vmcnt(0)
	s_waitcnt vmcnt(0)
.LBB0_1171:
	s_andn2_saveexec_b64 s[0:1], s[14:15]
	s_cbranch_execz .LBB0_1191
	s_mov_b64 s[0:1], exec
	buffer_wbl2 sc1
	s_waitcnt lgkmcnt(0)
	s_waitcnt vmcnt(0)
	v_mbcnt_lo_u32_b32 v1, s0, 0
	v_mbcnt_hi_u32_b32 v1, s1, v1
	v_cmp_eq_u32_e32 vcc, 0, v1
	s_and_saveexec_b64 s[14:15], vcc
	s_cbranch_execz .LBB0_1174
	s_bcnt1_i32_b64 s0, s[0:1]
	v_mov_b32_e32 v2, 0x3000
	v_mov_b32_e32 v3, s0
	global_atomic_add v2, v2, v3, s[74:75] offset:1024 sc0

; #define PG8_STAGE(bufoff, gbase, voff) do { const unsigned long long gb_ = (unsigned long long)(gbase); _Pragma("unroll") for (int _i = 0; _i < 2; ++_i) { unsigned keep_; \
;         asm volatile("s_mov_b32 m0, %2\n\ts_nop 0\n\tglobal_load_lds_dwordx4 %0, %1" : : "v"((voff)[_i]), "s"(gb_), "s"((unsigned)(size_t)(lds + (bufoff) + ldsw + _i * 8192)) : "memory", "m0"); (void)keep_; } } while (0)
; #define PG8_WAIT_V(n) asm volatile("s_waitcnt vmcnt(" #n ")" ::: "memory")
; #define PG8_BAR __builtin_amdgcn_s_barrier()
; template <class Epi, class Sched, bool ALIGN_EPI = false, bool SP2 = false>
; __device__ __forceinline__ void gemm_phase(PG8_LAS unsigned char* lds, const Gemm g, const Sched& S, const Epi& E) {
;     ...
;     const unsigned ldsw = (unsigned)wid * 1024u;
;     const int aoff = lds_byte(wr * 64 + fr, fq * 8), boff = lds_byte(wc * 32 + fr, fq * 8);
;     ...
;     if constexpr (SP2) {
;         PG8_STAGE(PG8_SB(0, 0), cB, voffB); PG8_STAGE(PG8_SB(0, 1), cB + hstepB, voffB); PG8_STAGE(PG8_SA(0, 0), cA, voffA); PG8_STAGE(PG8_SA(0, 1), cA + hstepA, voffA);
;         if (wr == 1) PG8_BAR;
;         PG8_WAIT_V(2); PG8_BAR;
;         PG8_STAGE(PG8_SB(1, 0), cB + kstep, voffB); PG8_STAGE(PG8_SA(1, 0), cA + kstep, voffA); PG8_STAGE(PG8_SB(1, 1), cB + hstepB + kstep, voffB);
;         PG8_WAIT_V(6); PG8_BAR;
.LBB0_1225:
	v_bfe_u32 v3, v200, 4, 2
	v_and_b32_e32 v2, 15, v200
	v_lshlrev_b32_e32 v1, 4, v3
	v_lshlrev_b32_e32 v5, 2, v200
	s_and_b32 s61, s0, 3
	v_lshl_or_b32 v4, v2, 6, v1
	s_lshl_b32 s0, s1, 13
	v_and_b32_e32 v5, 32, v5
	v_bitop3_b32 v4, v4, s0, v5 bitop3:0xde
	s_waitcnt vmcnt(23)
	v_lshlrev_b32_e32 v6, 6, v200
	s_movk_i32 s0, 0x3c0
	s_lshl_b32 s5, s1, 6
	v_and_or_b32 v1, v6, s0, v1
	s_lshl_b32 s0, s61, 12
	s_add_u32 s22, s74, 0x2000000
	s_addc_u32 s23, s75, 0
	s_add_u32 s24, s74, 0x200000
	v_or_b32_e32 v136, s5, v2
	v_lshlrev_b32_e32 v0, 3, v3
	s_addc_u32 s25, s75, 0
	v_mov_b32_e32 v137, 0
	v_bitop3_b32 v5, s0, v1, v5 bitop3:0xf6
	s_add_u32 s26, s74, 0xa000000
	v_lshl_or_b32 v138, s61, 5, v0
	v_or_b32_e32 v0, 16, v136
	v_mov_b32_e32 v1, v137
	s_addc_u32 s27, s75, 0
	v_lshlrev_b64 v[142:143], 9, v[0:1]
	v_or_b32_e32 v0, 32, v136
	s_add_u32 s0, s42, 0x80
	v_lshlrev_b64 v[144:145], 9, v[0:1]
	v_or_b32_e32 v0, 48, v136
	s_addc_u32 s1, s43, 0
	s_add_i32 s62, s53, 0x18000
	s_mov_b32 m0, s62
	s_nop 0
	global_load_lds_dwordx4 v172, s[0:1]
	s_add_i32 s63, s53, 0x1a000
	v_lshlrev_b64 v[146:147], 9, v[0:1]
	v_add_u32_e32 v0, 0x80, v136
	s_mov_b32 m0, s63
	s_nop 0
	global_load_lds_dwordx4 v174, s[0:1]
	s_add_u32 s0, s10, 0x80
	v_lshlrev_b64 v[148:149], 9, v[0:1]
	v_add_u32_e32 v0, 0x90, v136
	s_addc_u32 s1, s11, 0
	s_add_i32 s64, s53, 0x8000
	s_mov_b32 m0, s64
	s_nop 0
	global_load_lds_dwordx4 v139, s[0:1]
	s_add_i32 s65, s53, 0xa000
	v_lshlrev_b64 v[150:151], 9, v[0:1]
	v_add_u32_e32 v0, 0xa0, v136
	s_mov_b32 m0, s65
	s_nop 0
	global_load_lds_dwordx4 v173, s[0:1]
	s_add_u32 s0, s42, 0x80080
	v_lshlrev_b64 v[152:153], 9, v[0:1]
	v_add_u32_e32 v0, 0xb0, v136
	s_addc_u32 s1, s43, 0
	s_add_i32 s66, s53, 0x1c000
	s_mov_b32 m0, s66
	s_nop 0
	global_load_lds_dwordx4 v172, s[0:1]
	v_lshlrev_b64 v[154:155], 9, v[0:1]
	v_mov_b32_e32 v0, 0xcf
	s_add_i32 s67, s53, 0x1e000
	s_mov_b32 m0, s67
	s_nop 0
	global_load_lds_dwordx4 v174, s[0:1]
	v_bitop3_b32 v2, s5, v0, v2 bitop3:0xc8
	v_lshlrev_b32_e32 v0, 5, v3
	s_cmp_eq_u64 s[20:21], 0
	s_cbranch_scc1 .Lstag_skip_8
	s_barrier
.Lstag_skip_8:
	s_waitcnt vmcnt(8)
	s_barrier
	s_waitcnt vmcnt(6)
	s_add_i32 s68, s53, 0xc000
	v_lshl_add_u64 v[156:157], s[8:9], 0, v[0:1]
	v_add_u32_e32 v0, 0, v5
	s_cmpk_lt_u32 s4, 0x100
	v_add_u32_e32 v175, 0x10000, v0
	v_add_u32_e32 v176, 0x14000, v0
	v_add_u32_e32 v178, 0x18000, v0
	v_add_u32_e32 v179, 0x1c000, v0
	v_mbcnt_lo_u32_b32 v0, -1, 0
	s_cselect_b64 s[28:29], -1, 0
	v_cmp_eq_u32_e64 s[6:7], 0, v3
	v_lshlrev_b64 v[140:141], 9, v[136:137]
	s_add_i32 s69, s53, 0xe000
	s_ashr_i32 s70, s33, 31
	s_ashr_i32 s71, s2, 31
	v_lshl_add_u32 v137, v2, 2, s50
	v_mov_b64_e32 v[158:159], 0x200
	v_mov_b64_e32 v[160:161], 0x1ff
	v_add_u32_e32 v177, 0, v4
	v_mov_b32_e32 v180, 0x358637bd
	v_mbcnt_hi_u32_b32 v181, -1, v0
	s_mov_b32 s72, 0
	s_barrier
	s_branch .LBB0_1228

; __device__ __forceinline__ unsigned xb_ld(unsigned* p)              { return __hip_atomic_load(p, __ATOMIC_RELAXED, __HIP_MEMORY_SCOPE_AGENT); }
; __device__ __forceinline__ unsigned xb_add(unsigned* p, unsigned v) { return __hip_atomic_fetch_add(p, v, __ATOMIC_RELAXED, __HIP_MEMORY_SCOPE_AGENT); }
; #define XB_SPIN(cond, bar) do { unsigned _sp = 0; while (cond) { __builtin_amdgcn_s_sleep(1); \
;     if ((++_sp & 255u) == 0u) { if (xb_ld(&(bar)[XB_TMO])) break; if (_sp > XB_SPIN_CAP) { atomicAdd(&(bar)[XB_TMO], 1u); break; } } } } while (0)
; __device__ __forceinline__ void xcd_barrier(const XcdBarrier& b) {
;     ...
;         if (old + 1u == (gen + 1u) * nloc) {
;             __builtin_amdgcn_fence(__ATOMIC_RELEASE, "agent");
;             asm volatile("s_waitcnt vmcnt(0)" ::: "memory");
;             const unsigned og = xb_add(&bar[XB_TOP], 1u);
;             const unsigned tg = og / nx;
;             if (og + 1u == (tg + 1u) * nx) xb_add(&bar[XB_TOPGEN], 1u);
;             else XB_SPIN(xb_ld(&bar[XB_TOPGEN]) == tg, bar);
;             __builtin_amdgcn_fence(__ATOMIC_ACQUIRE, "agent");
;             xb_add(&bar[XB_XGEN(b.x)], 1u);
;             asm volatile("s_waitcnt vmcnt(0)" ::: "memory");
;         } else {
;             XB_SPIN(xb_ld(&bar[XB_XGEN(b.x)]) == gen, bar);
;             __builtin_amdgcn_fence(__ATOMIC_ACQUIRE, "agent");
;             asm volatile("s_waitcnt vmcnt(0)" ::: "memory");
;         }
.LBB0_1320:
	s_or_b64 exec, exec, s[18:19]
	s_xor_b64 s[4:5], s[20:21], -1
	s_and_saveexec_b64 s[16:17], s[4:5]
	s_xor_b64 s[16:17], exec, s[16:17]
	s_cbranch_execz .LBB0_1323
	s_mov_b64 s[16:17], exec
	v_mbcnt_lo_u32_b32 v0, s16, 0
	v_mbcnt_hi_u32_b32 v0, s17, v0
	v_cmp_eq_u32_e32 vcc, 0, v0
	s_and_b64 s[4:5], exec, vcc
	s_mov_b64 exec, s[4:5]
	s_cbranch_execz .LBB0_1323
	s_bcnt1_i32_b64 s4, s[16:17]
	v_mov_b32_e32 v0, 0
	v_mov_b32_e32 v1, s4
	global_atomic_add v0, v1, s[74:75] offset:512
.LBB0_1323:
	s_or_b64 exec, exec, s[0:1]
	s_waitcnt vmcnt(0)
	s_waitcnt vmcnt(0)
.LBB0_1324:
	s_andn2_saveexec_b64 s[0:1], s[14:15]
	s_cbranch_execz .LBB0_1344
	s_mov_b64 s[0:1], exec
	buffer_wbl2 sc1
	s_waitcnt lgkmcnt(0)
	s_waitcnt vmcnt(0)
	v_mbcnt_lo_u32_b32 v1, s0, 0
	v_mbcnt_hi_u32_b32 v1, s1, v1
	v_cmp_eq_u32_e32 vcc, 0, v1
	s_and_saveexec_b64 s[14:15], vcc
	s_cbranch_execz .LBB0_1327
	s_bcnt1_i32_b64 s0, s[0:1]
	v_mov_b32_e32 v2, 0x3000
	v_mov_b32_e32 v3, s0
	global_atomic_add v2, v2, v3, s[74:75] offset:1024 sc0

; #define PG8_STAGE(bufoff, gbase, voff) do { const unsigned long long gb_ = (unsigned long long)(gbase); _Pragma("unroll") for (int _i = 0; _i < 2; ++_i) { unsigned keep_; \
;         asm volatile("s_mov_b32 m0, %2\n\ts_nop 0\n\tglobal_load_lds_dwordx4 %0, %1" : : "v"((voff)[_i]), "s"(gb_), "s"((unsigned)(size_t)(lds + (bufoff) + ldsw + _i * 8192)) : "memory", "m0"); (void)keep_; } } while (0)
; #define PG8_WAIT_V(n) asm volatile("s_waitcnt vmcnt(" #n ")" ::: "memory")
; #define PG8_BAR __builtin_amdgcn_s_barrier()
; template <class Epi, class Sched, bool ALIGN_EPI = false, bool SP2 = false>
; __device__ __forceinline__ void gemm_phase(PG8_LAS unsigned char* lds, const Gemm g, const Sched& S, const Epi& E) {
;     ...
;     const unsigned ldsw = (unsigned)wid * 1024u;
;     const int aoff = lds_byte(wr * 64 + fr, fq * 8), boff = lds_byte(wc * 32 + fr, fq * 8);
;     ...
;     if constexpr (SP2) {
;         PG8_STAGE(PG8_SB(0, 0), cB, voffB); PG8_STAGE(PG8_SB(0, 1), cB + hstepB, voffB); PG8_STAGE(PG8_SA(0, 0), cA, voffA); PG8_STAGE(PG8_SA(0, 1), cA + hstepA, voffA);
;         if (wr == 1) PG8_BAR;
;         PG8_WAIT_V(2); PG8_BAR;
;         PG8_STAGE(PG8_SB(1, 0), cB + kstep, voffB); PG8_STAGE(PG8_SA(1, 0), cA + kstep, voffA); PG8_STAGE(PG8_SB(1, 1), cB + hstepB + kstep, voffB);
;         PG8_WAIT_V(6); PG8_BAR;
.LBB0_1374:
	v_and_b32_e32 v1, 15, v200
	v_lshlrev_b32_e32 v2, 1, v0
	v_lshlrev_b32_e32 v4, 2, v200
	s_lshl_b32 s20, s0, 6
	v_lshl_or_b32 v3, v1, 6, v2
	s_lshl_b32 s0, s0, 13
	v_and_b32_e32 v4, 32, v4
	v_bitop3_b32 v3, v3, s0, v4 bitop3:0xde
	s_lshl_b32 s0, s1, 5
	s_and_b32 s21, s0, 0x60
	v_lshlrev_b32_e32 v5, 6, v200
	s_movk_i32 s0, 0x3c0
	v_and_or_b32 v2, v5, s0, v2
	s_lshl_b32 s0, s21, 7
	s_add_u32 s52, s74, 0xe000000
	s_addc_u32 s53, s75, 0
	v_or_b32_e32 v128, s20, v1
	v_bitop3_b32 v2, s0, v2, v4 bitop3:0xf6
	s_mov_b32 s22, 0x160000
	s_and_b64 s[0:1], s[18:19], exec
	s_cselect_b32 s54, s22, 0x200000
	s_add_u32 s0, s34, 0x80
	v_mov_b32_e32 v131, 0
	v_or_b32_e32 v130, 16, v128
	s_addc_u32 s1, s35, 0
	s_add_i32 s55, s31, 0x18000
	s_mov_b32 m0, s55
	s_nop 0
	global_load_lds_dwordx4 v161, s[0:1]
	s_add_i32 s56, s31, 0x1a000
	v_lshlrev_b64 v[134:135], 8, v[130:131]
	v_or_b32_e32 v130, 32, v128
	s_mov_b32 m0, s56
	s_nop 0
	global_load_lds_dwordx4 v165, s[0:1]
	s_add_u32 s0, s8, 0x80
	v_lshlrev_b64 v[136:137], 8, v[130:131]
	v_or_b32_e32 v130, 48, v128
	s_addc_u32 s1, s9, 0
	s_add_i32 s57, s31, 0x8000
	s_mov_b32 m0, s57
	s_nop 0
	global_load_lds_dwordx4 v159, s[0:1]
	s_add_i32 s58, s31, 0xa000
	v_lshlrev_b64 v[138:139], 8, v[130:131]
	v_add_u32_e32 v130, 0x80, v128
	s_mov_b32 m0, s58
	s_nop 0
	global_load_lds_dwordx4 v163, s[0:1]
	s_add_u32 s0, s34, 0x80080
	v_lshlrev_b64 v[140:141], 8, v[130:131]
	v_add_u32_e32 v130, 0x90, v128
	s_addc_u32 s1, s35, 0
	s_add_i32 s59, s31, 0x1c000
	s_mov_b32 m0, s59
	s_nop 0
	global_load_lds_dwordx4 v161, s[0:1]
	v_lshlrev_b64 v[142:143], 8, v[130:131]
	v_add_u32_e32 v130, 0xa0, v128
	s_add_i32 s60, s31, 0x1e000
	s_mov_b32 m0, s60
	s_nop 0
	global_load_lds_dwordx4 v165, s[0:1]
	v_mov_b32_e32 v4, 0xcf
	v_lshlrev_b64 v[144:145], 8, v[130:131]
	v_add_u32_e32 v130, 0xb0, v128
	s_cmp_eq_u64 s[16:17], 0
	s_cbranch_scc1 .Lstag_skip_7
	s_barrier
.Lstag_skip_7:
	s_waitcnt vmcnt(8)
	s_barrier
	s_waitcnt vmcnt(6)
	s_add_i32 s61, s31, 0xc000
	v_bitop3_b32 v1, s20, v4, v1 bitop3:0xc8
	v_mov_b32_e32 v129, v131
	v_lshlrev_b64 v[146:147], 8, v[130:131]
	v_lshlrev_b32_e32 v130, 2, v0
	s_cmpk_lt_u32 s14, 0x100
	v_lshlrev_b64 v[132:133], 8, v[128:129]
	v_lshl_add_u64 v[148:149], s[6:7], 0, v[130:131]
	v_lshl_add_u32 v129, v1, 2, s5
	v_add_u32_e32 v1, 0, v2
	v_lshlrev_b32_e32 v130, 1, v0
	v_mbcnt_lo_u32_b32 v0, -1, 0
	s_cselect_b64 s[18:19], -1, 0
	s_add_i32 s62, s31, 0xe000
	s_ashr_i32 s63, s4, 31
	s_ashr_i32 s64, s2, 31
	v_mov_b64_e32 v[150:151], 0xb00
	v_mov_b64_e32 v[152:153], 0xaff
	s_movk_i32 s65, 0x161
	v_add_u32_e32 v167, 0x10000, v1
	v_add_u32_e32 v169, 0x14000, v1
	v_add_u32_e32 v172, 0, v3
	v_add_u32_e32 v173, 0x18000, v1
	v_add_u32_e32 v174, 0x1c000, v1
	v_mov_b32_e32 v175, 0x358637bd
	s_lshl_b32 s14, s21, 1
	v_mbcnt_hi_u32_b32 v176, -1, v0
	s_mov_b32 s66, s15
	s_barrier
	s_branch .LBB0_1377

; __device__ __forceinline__ unsigned xb_ld(unsigned* p)              { return __hip_atomic_load(p, __ATOMIC_RELAXED, __HIP_MEMORY_SCOPE_AGENT); }
; __device__ __forceinline__ unsigned xb_add(unsigned* p, unsigned v) { return __hip_atomic_fetch_add(p, v, __ATOMIC_RELAXED, __HIP_MEMORY_SCOPE_AGENT); }
; #define XB_SPIN(cond, bar) do { unsigned _sp = 0; while (cond) { __builtin_amdgcn_s_sleep(1); \
;     if ((++_sp & 255u) == 0u) { if (xb_ld(&(bar)[XB_TMO])) break; if (_sp > XB_SPIN_CAP) { atomicAdd(&(bar)[XB_TMO], 1u); break; } } } } while (0)
; __device__ __forceinline__ void xcd_barrier(const XcdBarrier& b) {
;     ...
;         if (old + 1u == (gen + 1u) * nloc) {
;             __builtin_amdgcn_fence(__ATOMIC_RELEASE, "agent");
;             asm volatile("s_waitcnt vmcnt(0)" ::: "memory");
;             const unsigned og = xb_add(&bar[XB_TOP], 1u);
;             const unsigned tg = og / nx;
;             if (og + 1u == (tg + 1u) * nx) xb_add(&bar[XB_TOPGEN], 1u);
;             else XB_SPIN(xb_ld(&bar[XB_TOPGEN]) == tg, bar);
;             __builtin_amdgcn_fence(__ATOMIC_ACQUIRE, "agent");
;             xb_add(&bar[XB_XGEN(b.x)], 1u);
;             asm volatile("s_waitcnt vmcnt(0)" ::: "memory");
;         } else {
;             XB_SPIN(xb_ld(&bar[XB_XGEN(b.x)]) == gen, bar);
;             __builtin_amdgcn_fence(__ATOMIC_ACQUIRE, "agent");
;             asm volatile("s_waitcnt vmcnt(0)" ::: "memory");
;         }
.LBB0_1449:
	s_or_b64 exec, exec, s[18:19]
	s_xor_b64 s[4:5], s[20:21], -1
	s_and_saveexec_b64 s[16:17], s[4:5]
	s_xor_b64 s[16:17], exec, s[16:17]
	s_cbranch_execz .LBB0_1452
	s_mov_b64 s[16:17], exec
	v_mbcnt_lo_u32_b32 v0, s16, 0
	v_mbcnt_hi_u32_b32 v0, s17, v0
	v_cmp_eq_u32_e32 vcc, 0, v0
	s_and_b64 s[4:5], exec, vcc
	s_mov_b64 exec, s[4:5]
	s_cbranch_execz .LBB0_1452
	s_bcnt1_i32_b64 s4, s[16:17]
	v_mov_b32_e32 v0, 0
	v_mov_b32_e32 v1, s4
	global_atomic_add v0, v1, s[74:75] offset:512
.LBB0_1452:
	s_or_b64 exec, exec, s[0:1]
	s_waitcnt vmcnt(0)
	s_waitcnt vmcnt(0)
.LBB0_1453:
	s_andn2_saveexec_b64 s[0:1], s[14:15]
	s_cbranch_execz .LBB0_1473
	s_mov_b64 s[0:1], exec
	buffer_wbl2 sc1
	s_waitcnt lgkmcnt(0)
	s_waitcnt vmcnt(0)
	v_mbcnt_lo_u32_b32 v1, s0, 0
	v_mbcnt_hi_u32_b32 v1, s1, v1
	v_cmp_eq_u32_e32 vcc, 0, v1
	s_and_saveexec_b64 s[14:15], vcc
	s_cbranch_execz .LBB0_1456
	s_bcnt1_i32_b64 s0, s[0:1]
	v_mov_b32_e32 v2, 0x3000
	v_mov_b32_e32 v3, s0
	global_atomic_add v2, v2, v3, s[74:75] offset:1024 sc0

; __device__ __forceinline__ unsigned xb_ld(unsigned* p)              { return __hip_atomic_load(p, __ATOMIC_RELAXED, __HIP_MEMORY_SCOPE_AGENT); }
; __device__ __forceinline__ unsigned xb_add(unsigned* p, unsigned v) { return __hip_atomic_fetch_add(p, v, __ATOMIC_RELAXED, __HIP_MEMORY_SCOPE_AGENT); }
; #define XB_SPIN(cond, bar) do { unsigned _sp = 0; while (cond) { __builtin_amdgcn_s_sleep(1); \
;     if ((++_sp & 255u) == 0u) { if (xb_ld(&(bar)[XB_TMO])) break; if (_sp > XB_SPIN_CAP) { atomicAdd(&(bar)[XB_TMO], 1u); break; } } } } while (0)
; __device__ __forceinline__ void xcd_barrier(const XcdBarrier& b) {
;     ...
;         if (old + 1u == (gen + 1u) * nloc) {
;             __builtin_amdgcn_fence(__ATOMIC_RELEASE, "agent");
;             asm volatile("s_waitcnt vmcnt(0)" ::: "memory");
;             const unsigned og = xb_add(&bar[XB_TOP], 1u);
;             const unsigned tg = og / nx;
;             if (og + 1u == (tg + 1u) * nx) xb_add(&bar[XB_TOPGEN], 1u);
;             else XB_SPIN(xb_ld(&bar[XB_TOPGEN]) == tg, bar);
;             __builtin_amdgcn_fence(__ATOMIC_ACQUIRE, "agent");
;             xb_add(&bar[XB_XGEN(b.x)], 1u);
;             asm volatile("s_waitcnt vmcnt(0)" ::: "memory");
;         } else {
;             XB_SPIN(xb_ld(&bar[XB_XGEN(b.x)]) == gen, bar);
;             __builtin_amdgcn_fence(__ATOMIC_ACQUIRE, "agent");
;             asm volatile("s_waitcnt vmcnt(0)" ::: "memory");
;         }
.LBB0_1570:
	s_or_b64 exec, exec, s[18:19]
	s_xor_b64 s[4:5], s[20:21], -1
	s_and_saveexec_b64 s[16:17], s[4:5]
	s_xor_b64 s[16:17], exec, s[16:17]
	s_cbranch_execz .LBB0_1573
	s_mov_b64 s[16:17], exec
	v_mbcnt_lo_u32_b32 v0, s16, 0
	v_mbcnt_hi_u32_b32 v0, s17, v0
	v_cmp_eq_u32_e32 vcc, 0, v0
	s_and_b64 s[4:5], exec, vcc
	s_mov_b64 exec, s[4:5]
	s_cbranch_execz .LBB0_1573
	s_bcnt1_i32_b64 s4, s[16:17]
	v_mov_b32_e32 v0, 0
	v_mov_b32_e32 v1, s4
	global_atomic_add v0, v1, s[74:75] offset:512
.LBB0_1573:
	s_or_b64 exec, exec, s[0:1]
	s_waitcnt vmcnt(0)
	s_waitcnt vmcnt(0)
.LBB0_1574:
	s_andn2_saveexec_b64 s[0:1], s[14:15]
	s_cbranch_execz .LBB0_1594
	s_mov_b64 s[0:1], exec
	buffer_wbl2 sc1
	s_waitcnt lgkmcnt(0)
	s_waitcnt vmcnt(0)
	v_mbcnt_lo_u32_b32 v1, s0, 0
	v_mbcnt_hi_u32_b32 v1, s1, v1
	v_cmp_eq_u32_e32 vcc, 0, v1
	s_and_saveexec_b64 s[14:15], vcc
	s_cbranch_execz .LBB0_1577
	s_bcnt1_i32_b64 s0, s[0:1]
	v_mov_b32_e32 v2, 0x3000
	v_mov_b32_e32 v3, s0
	global_atomic_add v2, v2, v3, s[74:75] offset:1024 sc0

; #define PG8_STAGE(bufoff, gbase, voff) do { const unsigned long long gb_ = (unsigned long long)(gbase); _Pragma("unroll") for (int _i = 0; _i < 2; ++_i) { unsigned keep_; \
;         asm volatile("s_mov_b32 m0, %2\n\ts_nop 0\n\tglobal_load_lds_dwordx4 %0, %1" : : "v"((voff)[_i]), "s"(gb_), "s"((unsigned)(size_t)(lds + (bufoff) + ldsw + _i * 8192)) : "memory", "m0"); (void)keep_; } } while (0)
; #define PG8_WAIT_V(n) asm volatile("s_waitcnt vmcnt(" #n ")" ::: "memory")
; #define PG8_BAR __builtin_amdgcn_s_barrier()
;     __device__ __forceinline__ void operator()(const f32x4 (&acc)[2][2][4][2], const Unit& u, int wr, int wc, int fr, int fq) const {
;     ...
;             for (int n = 0; n < 2; ++n) bvv[bj][n] = bp ? *(const f32x4*)(bp + bj * HALF + 4 * n) : (f32x4){0.f, 0.f, 0.f, 0.f};
; template <class Epi, class Sched, bool ALIGN_EPI = false, bool SP2 = false>
; __device__ __forceinline__ void gemm_phase(PG8_LAS unsigned char* lds, const Gemm g, const Sched& S, const Epi& E) {
;     ...
;     if constexpr (SP2) {
;         PG8_STAGE(PG8_SB(0, 0), cB, voffB); PG8_STAGE(PG8_SB(0, 1), cB + hstepB, voffB); PG8_STAGE(PG8_SA(0, 0), cA, voffA); PG8_STAGE(PG8_SA(0, 1), cA + hstepA, voffA);
;         if (wr == 1) PG8_BAR;
;         PG8_WAIT_V(2); PG8_BAR;
;         PG8_STAGE(PG8_SB(1, 0), cB + kstep, voffB); PG8_STAGE(PG8_SA(1, 0), cA + kstep, voffA); PG8_STAGE(PG8_SB(1, 1), cB + hstepB + kstep, voffB);
;         PG8_WAIT_V(6); PG8_BAR;
.LBB0_1624:
	v_and_b32_e32 v1, 15, v200
	v_lshlrev_b32_e32 v2, 1, v0
	v_lshlrev_b32_e32 v4, 2, v200
	s_lshl_b32 s9, s1, 6
	v_lshl_or_b32 v3, v1, 6, v2
	s_lshl_b32 s1, s1, 13
	v_and_b32_e32 v4, 32, v4
	s_lshl_b32 s0, s0, 5
	v_bitop3_b32 v5, v3, s1, v4 bitop3:0xde
	s_and_b32 s26, s0, 0x60
	v_lshlrev_b32_e32 v3, 6, v200
	s_movk_i32 s0, 0x3c0
	v_and_or_b32 v2, v3, s0, v2
	s_lshl_b32 s0, s26, 7
	v_bitop3_b32 v4, s0, v2, v4 bitop3:0xf6
	v_mov_b32_e32 v2, 0x160000
	v_readlane_b32 s0, v254, 19
	v_mov_b32_e32 v145, 0
	v_mul_u32_u24_e32 v2, s0, v2
	v_cndmask_b32_e64 v2, v2, 0, s[24:25]
	v_lshlrev_b32_e32 v144, 1, v2
	v_lshl_add_u64 v[2:3], s[74:75], 0, v[144:145]
	s_mov_b64 s[0:1], 0xe000000
	v_lshl_add_u64 v[146:147], v[2:3], 0, s[0:1]
	s_add_u32 s0, s40, 0x80
	s_addc_u32 s1, s41, 0
	s_add_i32 s62, s39, 0x18000
	s_mov_b32 m0, s62
	s_nop 0
	global_load_lds_dwordx4 v161, s[0:1]
	s_add_i32 s63, s39, 0x1a000
	s_mov_b32 m0, s63
	s_nop 0
	global_load_lds_dwordx4 v169, s[0:1]
	s_add_u32 s0, s42, 0x80
	s_addc_u32 s1, s43, 0
	s_add_i32 s64, s39, 0x8000
	s_mov_b32 m0, s64
	s_nop 0
	global_load_lds_dwordx4 v149, s[0:1]
	s_add_i32 s65, s39, 0xa000
	s_mov_b32 m0, s65
	s_nop 0
	global_load_lds_dwordx4 v167, s[0:1]
	s_add_u32 s0, s40, 0x80080
	s_addc_u32 s1, s41, 0
	s_add_i32 s66, s39, 0x1c000
	s_mov_b32 m0, s66
	s_nop 0
	global_load_lds_dwordx4 v161, s[0:1]
	s_add_i32 s67, s39, 0x1e000
	s_add_i32 s68, s39, 0xc000
	s_mov_b32 m0, s67
	s_nop 0
	global_load_lds_dwordx4 v169, s[0:1]
	s_cmp_eq_u64 s[22:23], 0
	s_cbranch_scc1 .Lstag_skip_5
	s_barrier
.Lstag_skip_5:
	s_cmpk_lt_u32 s20, 0x100
	s_waitcnt vmcnt(8)
	s_barrier
	s_waitcnt vmcnt(6)
	s_cselect_b64 s[24:25], -1, 0
	s_add_i32 s69, s39, 0xe000
	v_mov_b32_e32 v2, 0xcf
	s_ashr_i32 s70, s4, 31
	s_ashr_i32 s71, s2, 31
	v_or_b32_e32 v171, s9, v1
	v_or_b32_e32 v148, s26, v0
	v_bitop3_b32 v1, s9, v2, v1 bitop3:0xc8
	s_cmp_eq_u64 s[12:13], 0
	v_lshlrev_b32_e32 v144, 2, v0
	v_add_u32_e32 v0, 0, v4
	s_cselect_b64 s[26:27], -1, 0
	v_lshl_add_u64 v[150:151], s[6:7], 0, v[144:145]
	v_lshl_add_u32 v172, v1, 2, s5
	v_mov_b64_e32 v[152:153], 0x280
	v_mov_b64_e32 v[154:155], 0x27f
	s_movk_i32 s72, 0x51
	v_add_u32_e32 v173, 0x10000, v0
	v_add_u32_e32 v174, 0x14000, v0
	v_add_u32_e32 v175, 0, v5
	v_add_u32_e32 v176, 0x18000, v0
	v_add_u32_e32 v177, 0x1c000, v0
	v_lshlrev_b32_e32 v144, 2, v148
	v_mov_b32_e32 v178, 0x358637bd
	s_movk_i32 s73, 0x1400
	v_mbcnt_lo_u32_b32 v179, -1, 0
	s_mov_b32 s76, 0
	s_barrier
	s_branch .LBB0_1627

; __device__ __forceinline__ unsigned xb_ld(unsigned* p)              { return __hip_atomic_load(p, __ATOMIC_RELAXED, __HIP_MEMORY_SCOPE_AGENT); }
; __device__ __forceinline__ unsigned xb_add(unsigned* p, unsigned v) { return __hip_atomic_fetch_add(p, v, __ATOMIC_RELAXED, __HIP_MEMORY_SCOPE_AGENT); }
; #define XB_SPIN(cond, bar) do { unsigned _sp = 0; while (cond) { __builtin_amdgcn_s_sleep(1); \
;     if ((++_sp & 255u) == 0u) { if (xb_ld(&(bar)[XB_TMO])) break; if (_sp > XB_SPIN_CAP) { atomicAdd(&(bar)[XB_TMO], 1u); break; } } } } while (0)
; __device__ __forceinline__ void xcd_barrier(const XcdBarrier& b) {
;     ...
;         if (old + 1u == (gen + 1u) * nloc) {
;             __builtin_amdgcn_fence(__ATOMIC_RELEASE, "agent");
;             asm volatile("s_waitcnt vmcnt(0)" ::: "memory");
;             const unsigned og = xb_add(&bar[XB_TOP], 1u);
;             const unsigned tg = og / nx;
;             if (og + 1u == (tg + 1u) * nx) xb_add(&bar[XB_TOPGEN], 1u);
;             else XB_SPIN(xb_ld(&bar[XB_TOPGEN]) == tg, bar);
;             __builtin_amdgcn_fence(__ATOMIC_ACQUIRE, "agent");
;             xb_add(&bar[XB_XGEN(b.x)], 1u);
;             asm volatile("s_waitcnt vmcnt(0)" ::: "memory");
;         } else {
;             XB_SPIN(xb_ld(&bar[XB_XGEN(b.x)]) == gen, bar);
;             __builtin_amdgcn_fence(__ATOMIC_ACQUIRE, "agent");
;             asm volatile("s_waitcnt vmcnt(0)" ::: "memory");
;         }
.LBB0_1706:
	s_or_b64 exec, exec, s[16:17]
	s_xor_b64 s[4:5], s[18:19], -1
	s_and_saveexec_b64 s[14:15], s[4:5]
	s_xor_b64 s[14:15], exec, s[14:15]
	s_cbranch_execz .LBB0_1709
	s_mov_b64 s[14:15], exec
	v_mbcnt_lo_u32_b32 v0, s14, 0
	v_mbcnt_hi_u32_b32 v0, s15, v0
	v_cmp_eq_u32_e32 vcc, 0, v0
	s_and_b64 s[4:5], exec, vcc
	s_mov_b64 exec, s[4:5]
	s_cbranch_execz .LBB0_1709
	s_bcnt1_i32_b64 s4, s[14:15]
	v_mov_b32_e32 v0, 0
	v_mov_b32_e32 v1, s4
	global_atomic_add v0, v1, s[74:75] offset:512
.LBB0_1709:
	s_or_b64 exec, exec, s[0:1]
	s_waitcnt vmcnt(0)
	s_waitcnt vmcnt(0)
.LBB0_1710:
	s_andn2_saveexec_b64 s[0:1], s[12:13]
	s_cbranch_execz .LBB0_1730
	s_mov_b64 s[0:1], exec
	buffer_wbl2 sc1
	s_waitcnt lgkmcnt(0)
	s_waitcnt vmcnt(0)
	v_mbcnt_lo_u32_b32 v1, s0, 0
	v_mbcnt_hi_u32_b32 v1, s1, v1
	v_cmp_eq_u32_e32 vcc, 0, v1
	s_and_saveexec_b64 s[12:13], vcc
	s_cbranch_execz .LBB0_1713
	s_bcnt1_i32_b64 s0, s[0:1]
	v_mov_b32_e32 v2, 0x3000
	v_mov_b32_e32 v3, s0
	global_atomic_add v2, v2, v3, s[74:75] offset:1024 sc0

; __device__ __forceinline__ unsigned xb_ld(unsigned* p)              { return __hip_atomic_load(p, __ATOMIC_RELAXED, __HIP_MEMORY_SCOPE_AGENT); }
; __device__ __forceinline__ unsigned xb_add(unsigned* p, unsigned v) { return __hip_atomic_fetch_add(p, v, __ATOMIC_RELAXED, __HIP_MEMORY_SCOPE_AGENT); }
; #define XB_SPIN(cond, bar) do { unsigned _sp = 0; while (cond) { __builtin_amdgcn_s_sleep(1); \
;     if ((++_sp & 255u) == 0u) { if (xb_ld(&(bar)[XB_TMO])) break; if (_sp > XB_SPIN_CAP) { atomicAdd(&(bar)[XB_TMO], 1u); break; } } } } while (0)
; __device__ __forceinline__ void xcd_barrier(const XcdBarrier& b) {
;     ...
;         if (old + 1u == (gen + 1u) * nloc) {
;             __builtin_amdgcn_fence(__ATOMIC_RELEASE, "agent");
;             asm volatile("s_waitcnt vmcnt(0)" ::: "memory");
;             const unsigned og = xb_add(&bar[XB_TOP], 1u);
;             const unsigned tg = og / nx;
;             if (og + 1u == (tg + 1u) * nx) xb_add(&bar[XB_TOPGEN], 1u);
;             else XB_SPIN(xb_ld(&bar[XB_TOPGEN]) == tg, bar);
;             __builtin_amdgcn_fence(__ATOMIC_ACQUIRE, "agent");
;             xb_add(&bar[XB_XGEN(b.x)], 1u);
;             asm volatile("s_waitcnt vmcnt(0)" ::: "memory");
;         } else {
;             XB_SPIN(xb_ld(&bar[XB_XGEN(b.x)]) == gen, bar);
;             __builtin_amdgcn_fence(__ATOMIC_ACQUIRE, "agent");
;             asm volatile("s_waitcnt vmcnt(0)" ::: "memory");
;         }
.LBB0_1780:
	s_or_b64 exec, exec, s[16:17]
	s_xor_b64 s[4:5], s[18:19], -1
	s_and_saveexec_b64 s[14:15], s[4:5]
	s_xor_b64 s[14:15], exec, s[14:15]
	s_cbranch_execz .LBB0_1783
	s_mov_b64 s[14:15], exec
	v_mbcnt_lo_u32_b32 v0, s14, 0
	v_mbcnt_hi_u32_b32 v0, s15, v0
	v_cmp_eq_u32_e32 vcc, 0, v0
	s_and_b64 s[4:5], exec, vcc
	s_mov_b64 exec, s[4:5]
	s_cbranch_execz .LBB0_1783
	s_bcnt1_i32_b64 s4, s[14:15]
	v_mov_b32_e32 v0, 0
	v_mov_b32_e32 v1, s4
	global_atomic_add v0, v1, s[74:75] offset:512
.LBB0_1783:
	s_or_b64 exec, exec, s[0:1]
	s_waitcnt vmcnt(0)
	s_waitcnt vmcnt(0)
.LBB0_1784:
	s_andn2_saveexec_b64 s[0:1], s[12:13]
	s_cbranch_execz .LBB0_1804
	s_mov_b64 s[0:1], exec
	buffer_wbl2 sc1
	s_waitcnt lgkmcnt(0)
	s_waitcnt vmcnt(0)
	v_mbcnt_lo_u32_b32 v1, s0, 0
	v_mbcnt_hi_u32_b32 v1, s1, v1
	v_cmp_eq_u32_e32 vcc, 0, v1
	s_and_saveexec_b64 s[12:13], vcc
	s_cbranch_execz .LBB0_1787
	s_bcnt1_i32_b64 s0, s[0:1]
	v_mov_b32_e32 v2, 0x3000
	v_mov_b32_e32 v3, s0
	global_atomic_add v2, v2, v3, s[74:75] offset:1024 sc0

; #define PG8_STAGE(bufoff, gbase, voff) do { const unsigned long long gb_ = (unsigned long long)(gbase); _Pragma("unroll") for (int _i = 0; _i < 2; ++_i) { unsigned keep_; \
;         asm volatile("s_mov_b32 m0, %2\n\ts_nop 0\n\tglobal_load_lds_dwordx4 %0, %1" : : "v"((voff)[_i]), "s"(gb_), "s"((unsigned)(size_t)(lds + (bufoff) + ldsw + _i * 8192)) : "memory", "m0"); (void)keep_; } } while (0)
; #define PG8_WAIT_V(n) asm volatile("s_waitcnt vmcnt(" #n ")" ::: "memory")
; #define PG8_BAR __builtin_amdgcn_s_barrier()
;     __device__ __forceinline__ void operator()(const f32x4 (&acc)[2][2][4][2], const Unit& u, int wr, int wc, int fr, int fq) const {
;     ...
;             for (int n = 0; n < 2; ++n) bv[bj][n] = bias ? *(const f32x4*)(bias + col0 + bj * HALF + 4 * n) : (f32x4){0.f, 0.f, 0.f, 0.f};
; template <class Epi, class Sched, bool ALIGN_EPI = false, bool SP2 = false>
; __device__ __forceinline__ void gemm_phase(PG8_LAS unsigned char* lds, const Gemm g, const Sched& S, const Epi& E) {
;     ...
;     if constexpr (SP2) {
;         PG8_STAGE(PG8_SB(0, 0), cB, voffB); PG8_STAGE(PG8_SB(0, 1), cB + hstepB, voffB); PG8_STAGE(PG8_SA(0, 0), cA, voffA); PG8_STAGE(PG8_SA(0, 1), cA + hstepA, voffA);
;         if (wr == 1) PG8_BAR;
;         PG8_WAIT_V(2); PG8_BAR;
;         PG8_STAGE(PG8_SB(1, 0), cB + kstep, voffB); PG8_STAGE(PG8_SA(1, 0), cA + kstep, voffA); PG8_STAGE(PG8_SB(1, 1), cB + hstepB + kstep, voffB);
;         PG8_WAIT_V(6); PG8_BAR;
.LBB0_1815:
	s_add_u32 s20, s74, 0x6000000
	s_addc_u32 s21, s75, 0
	s_add_u32 s22, s74, 0x2000000
	s_addc_u32 s23, s75, 0
	v_bfe_u32 v0, v200, 4, 2
	s_add_u32 s24, s74, 0x200000
	v_and_b32_e32 v1, 15, v200
	v_lshlrev_b32_e32 v3, 4, v0
	v_lshlrev_b32_e32 v4, 2, v200
	s_addc_u32 s25, s75, 0
	s_and_b32 s58, s0, 3
	v_lshl_or_b32 v202, s1, 6, v1
	v_lshl_or_b32 v1, v1, 6, v3
	s_lshl_b32 s0, s1, 13
	v_and_b32_e32 v4, 32, v4
	v_bitop3_b32 v5, v1, s0, v4 bitop3:0xde
	v_lshlrev_b32_e32 v1, 6, v200
	s_movk_i32 s0, 0x3c0
	v_and_or_b32 v1, v1, s0, v3
	s_lshl_b32 s0, s58, 12
	v_mov_b32_e32 v203, 0
	v_lshlrev_b32_e32 v2, 3, v0
	v_bitop3_b32 v3, s0, v1, v4 bitop3:0xf6
	s_add_u32 s0, s10, 0x80
	v_cmp_eq_u32_e64 s[6:7], 0, v0
	v_or_b32_e32 v0, 16, v202
	v_mov_b32_e32 v1, v203
	s_addc_u32 s1, s11, 0
	s_add_i32 s59, s41, 0x18000
	s_mov_b32 m0, s59
	s_nop 0
	global_load_lds_dwordx4 v205, s[0:1]
	s_add_i32 s60, s41, 0x1a000
	v_lshlrev_b64 v[208:209], 9, v[0:1]
	v_or_b32_e32 v0, 32, v202
	s_mov_b32 m0, s60
	s_nop 0
	global_load_lds_dwordx4 v231, s[0:1]
	s_add_u32 s0, s44, 0x80
	v_lshlrev_b64 v[210:211], 9, v[0:1]
	v_or_b32_e32 v0, 48, v202
	s_addc_u32 s1, s45, 0
	s_add_i32 s61, s41, 0x8000
	s_mov_b32 m0, s61
	s_nop 0
	global_load_lds_dwordx4 v201, s[0:1]
	s_add_i32 s62, s41, 0xa000
	v_lshlrev_b64 v[212:213], 9, v[0:1]
	v_add_u32_e32 v0, 0x80, v202
	s_mov_b32 m0, s62
	s_nop 0
	global_load_lds_dwordx4 v230, s[0:1]
	s_add_u32 s0, s10, 0x80080
	v_lshlrev_b64 v[214:215], 9, v[0:1]
	v_add_u32_e32 v0, 0x90, v202
	s_addc_u32 s1, s11, 0
	s_add_i32 s63, s41, 0x1c000
	s_mov_b32 m0, s63
	s_nop 0
	global_load_lds_dwordx4 v205, s[0:1]
	s_add_i32 s64, s41, 0x1e000
	s_add_i32 s65, s41, 0xc000
	v_lshlrev_b64 v[216:217], 9, v[0:1]
	v_add_u32_e32 v0, 0xa0, v202
	s_mov_b32 m0, s64
	s_nop 0
	global_load_lds_dwordx4 v231, s[0:1]
	v_lshlrev_b64 v[218:219], 9, v[0:1]
	v_add_u32_e32 v0, 0xb0, v202
	s_cmp_eq_u64 s[18:19], 0
	s_cbranch_scc1 .Lstag_skip_4
	s_barrier
.Lstag_skip_4:
	s_cmpk_lt_u32 s8, 0x100
	s_waitcnt vmcnt(8)
	s_barrier
	s_waitcnt vmcnt(6)
	s_cselect_b64 s[26:27], -1, 0
	v_lshlrev_b64 v[220:221], 9, v[0:1]
	s_add_i32 s66, s41, 0xe000
	s_ashr_i32 s67, s4, 31
	s_ashr_i32 s68, s2, 31
	v_add_u32_e32 v0, 0, v3
	v_lshlrev_b64 v[206:207], 9, v[202:203]
	s_cmp_lg_u64 s[14:15], 0
	v_add_u32_e32 v203, 0x10000, v0
	v_add_u32_e32 v232, 0x14000, v0
	v_add_u32_e32 v234, 0x18000, v0
	v_add_u32_e32 v235, 0x1c000, v0
	v_mbcnt_lo_u32_b32 v0, -1, 0
	v_lshl_or_b32 v204, s58, 5, v2
	s_cselect_b64 s[28:29], -1, 0
	v_mov_b64_e32 v[222:223], 0x200
	v_mov_b64_e32 v[224:225], 0x1ff
	v_add_u32_e32 v233, 0, v5
	v_mbcnt_hi_u32_b32 v236, -1, v0
	s_mov_b32 s69, 0
	s_barrier
	s_branch .LBB0_1818

; __device__ __forceinline__ unsigned xb_ld(unsigned* p)              { return __hip_atomic_load(p, __ATOMIC_RELAXED, __HIP_MEMORY_SCOPE_AGENT); }
; __device__ __forceinline__ unsigned xb_add(unsigned* p, unsigned v) { return __hip_atomic_fetch_add(p, v, __ATOMIC_RELAXED, __HIP_MEMORY_SCOPE_AGENT); }
; #define XB_SPIN(cond, bar) do { unsigned _sp = 0; while (cond) { __builtin_amdgcn_s_sleep(1); \
;     if ((++_sp & 255u) == 0u) { if (xb_ld(&(bar)[XB_TMO])) break; if (_sp > XB_SPIN_CAP) { atomicAdd(&(bar)[XB_TMO], 1u); break; } } } } while (0)
; __device__ __forceinline__ void xcd_barrier(const XcdBarrier& b) {
;     ...
;         if (old + 1u == (gen + 1u) * nloc) {
;             __builtin_amdgcn_fence(__ATOMIC_RELEASE, "agent");
;             asm volatile("s_waitcnt vmcnt(0)" ::: "memory");
;             const unsigned og = xb_add(&bar[XB_TOP], 1u);
;             const unsigned tg = og / nx;
;             if (og + 1u == (tg + 1u) * nx) xb_add(&bar[XB_TOPGEN], 1u);
;             else XB_SPIN(xb_ld(&bar[XB_TOPGEN]) == tg, bar);
;             __builtin_amdgcn_fence(__ATOMIC_ACQUIRE, "agent");
;             xb_add(&bar[XB_XGEN(b.x)], 1u);
;             asm volatile("s_waitcnt vmcnt(0)" ::: "memory");
;         } else {
;             XB_SPIN(xb_ld(&bar[XB_XGEN(b.x)]) == gen, bar);
;             __builtin_amdgcn_fence(__ATOMIC_ACQUIRE, "agent");
;             asm volatile("s_waitcnt vmcnt(0)" ::: "memory");
;         }
.LBB0_1886:
	s_or_b64 exec, exec, s[18:19]
	s_xor_b64 s[4:5], s[20:21], -1
	s_and_saveexec_b64 s[16:17], s[4:5]
	s_xor_b64 s[16:17], exec, s[16:17]
	s_cbranch_execz .LBB0_1889
	s_mov_b64 s[16:17], exec
	v_mbcnt_lo_u32_b32 v0, s16, 0
	v_mbcnt_hi_u32_b32 v0, s17, v0
	v_cmp_eq_u32_e32 vcc, 0, v0
	s_and_b64 s[4:5], exec, vcc
	s_mov_b64 exec, s[4:5]
	s_cbranch_execz .LBB0_1889
	s_bcnt1_i32_b64 s4, s[16:17]
	v_mov_b32_e32 v0, 0
	v_mov_b32_e32 v1, s4
	global_atomic_add v0, v1, s[74:75] offset:512
.LBB0_1889:
	s_or_b64 exec, exec, s[0:1]
	s_waitcnt vmcnt(0)
	s_waitcnt vmcnt(0)
.LBB0_1890:
	s_andn2_saveexec_b64 s[0:1], s[14:15]
	s_cbranch_execz .LBB0_1910
	s_mov_b64 s[0:1], exec
	buffer_wbl2 sc1
	s_waitcnt lgkmcnt(0)
	s_waitcnt vmcnt(0)
	v_mbcnt_lo_u32_b32 v1, s0, 0
	v_mbcnt_hi_u32_b32 v1, s1, v1
	v_cmp_eq_u32_e32 vcc, 0, v1
	s_and_saveexec_b64 s[14:15], vcc
	s_cbranch_execz .LBB0_1893
	s_bcnt1_i32_b64 s0, s[0:1]
	v_mov_b32_e32 v2, 0x3000
	v_mov_b32_e32 v3, s0
	global_atomic_add v2, v2, v3, s[74:75] offset:1024 sc0

; __device__ __forceinline__ unsigned xb_ld(unsigned* p)              { return __hip_atomic_load(p, __ATOMIC_RELAXED, __HIP_MEMORY_SCOPE_AGENT); }
; __device__ __forceinline__ unsigned xb_add(unsigned* p, unsigned v) { return __hip_atomic_fetch_add(p, v, __ATOMIC_RELAXED, __HIP_MEMORY_SCOPE_AGENT); }
; #define XB_SPIN(cond, bar) do { unsigned _sp = 0; while (cond) { __builtin_amdgcn_s_sleep(1); \
;     if ((++_sp & 255u) == 0u) { if (xb_ld(&(bar)[XB_TMO])) break; if (_sp > XB_SPIN_CAP) { atomicAdd(&(bar)[XB_TMO], 1u); break; } } } } while (0)
; __device__ __forceinline__ void xcd_barrier(const XcdBarrier& b) {
;     ...
;         if (old + 1u == (gen + 1u) * nloc) {
;             __builtin_amdgcn_fence(__ATOMIC_RELEASE, "agent");
;             asm volatile("s_waitcnt vmcnt(0)" ::: "memory");
;             const unsigned og = xb_add(&bar[XB_TOP], 1u);
;             const unsigned tg = og / nx;
;             if (og + 1u == (tg + 1u) * nx) xb_add(&bar[XB_TOPGEN], 1u);
;             else XB_SPIN(xb_ld(&bar[XB_TOPGEN]) == tg, bar);
;             __builtin_amdgcn_fence(__ATOMIC_ACQUIRE, "agent");
;             xb_add(&bar[XB_XGEN(b.x)], 1u);
;             asm volatile("s_waitcnt vmcnt(0)" ::: "memory");
;         } else {
;             XB_SPIN(xb_ld(&bar[XB_XGEN(b.x)]) == gen, bar);
;             __builtin_amdgcn_fence(__ATOMIC_ACQUIRE, "agent");
;             asm volatile("s_waitcnt vmcnt(0)" ::: "memory");
;         }
.LBB0_2039:
	s_or_b64 exec, exec, s[18:19]
	s_xor_b64 s[4:5], s[20:21], -1
	s_and_saveexec_b64 s[16:17], s[4:5]
	s_xor_b64 s[16:17], exec, s[16:17]
	s_cbranch_execz .LBB0_2042
	s_mov_b64 s[16:17], exec
	v_mbcnt_lo_u32_b32 v0, s16, 0
	v_mbcnt_hi_u32_b32 v0, s17, v0
	v_cmp_eq_u32_e32 vcc, 0, v0
	s_and_b64 s[4:5], exec, vcc
	s_mov_b64 exec, s[4:5]
	s_cbranch_execz .LBB0_2042
	s_bcnt1_i32_b64 s4, s[16:17]
	v_mov_b32_e32 v0, 0
	v_mov_b32_e32 v1, s4
	global_atomic_add v0, v1, s[74:75] offset:512
.LBB0_2042:
	s_or_b64 exec, exec, s[0:1]
	s_waitcnt vmcnt(0)
	s_waitcnt vmcnt(0)
.LBB0_2043:
	s_andn2_saveexec_b64 s[0:1], s[14:15]
	s_cbranch_execz .LBB0_2063
	s_mov_b64 s[0:1], exec
	buffer_wbl2 sc1
	s_waitcnt lgkmcnt(0)
	s_waitcnt vmcnt(0)
	v_mbcnt_lo_u32_b32 v1, s0, 0
	v_mbcnt_hi_u32_b32 v1, s1, v1
	v_cmp_eq_u32_e32 vcc, 0, v1
	s_and_saveexec_b64 s[14:15], vcc
	s_cbranch_execz .LBB0_2046
	s_bcnt1_i32_b64 s0, s[0:1]
	v_mov_b32_e32 v2, 0x3000
	v_mov_b32_e32 v3, s0
	global_atomic_add v2, v2, v3, s[74:75] offset:1024 sc0

; __device__ __forceinline__ unsigned xb_ld(unsigned* p)              { return __hip_atomic_load(p, __ATOMIC_RELAXED, __HIP_MEMORY_SCOPE_AGENT); }
; __device__ __forceinline__ unsigned xb_add(unsigned* p, unsigned v) { return __hip_atomic_fetch_add(p, v, __ATOMIC_RELAXED, __HIP_MEMORY_SCOPE_AGENT); }
; #define XB_SPIN(cond, bar) do { unsigned _sp = 0; while (cond) { __builtin_amdgcn_s_sleep(1); \
;     if ((++_sp & 255u) == 0u) { if (xb_ld(&(bar)[XB_TMO])) break; if (_sp > XB_SPIN_CAP) { atomicAdd(&(bar)[XB_TMO], 1u); break; } } } } while (0)
; __device__ __forceinline__ void xcd_barrier(const XcdBarrier& b) {
;     ...
;         if (old + 1u == (gen + 1u) * nloc) {
;             __builtin_amdgcn_fence(__ATOMIC_RELEASE, "agent");
;             asm volatile("s_waitcnt vmcnt(0)" ::: "memory");
;             const unsigned og = xb_add(&bar[XB_TOP], 1u);
;             const unsigned tg = og / nx;
;             if (og + 1u == (tg + 1u) * nx) xb_add(&bar[XB_TOPGEN], 1u);
;             else XB_SPIN(xb_ld(&bar[XB_TOPGEN]) == tg, bar);
;             __builtin_amdgcn_fence(__ATOMIC_ACQUIRE, "agent");
;             xb_add(&bar[XB_XGEN(b.x)], 1u);
;             asm volatile("s_waitcnt vmcnt(0)" ::: "memory");
;         } else {
;             XB_SPIN(xb_ld(&bar[XB_XGEN(b.x)]) == gen, bar);
;             __builtin_amdgcn_fence(__ATOMIC_ACQUIRE, "agent");
;             asm volatile("s_waitcnt vmcnt(0)" ::: "memory");
;         }
.LBB0_2160:
	s_or_b64 exec, exec, s[18:19]
	s_xor_b64 s[4:5], s[20:21], -1
	s_and_saveexec_b64 s[16:17], s[4:5]
	s_xor_b64 s[16:17], exec, s[16:17]
	s_cbranch_execz .LBB0_2163
	s_mov_b64 s[16:17], exec
	v_mbcnt_lo_u32_b32 v0, s16, 0
	v_mbcnt_hi_u32_b32 v0, s17, v0
	v_cmp_eq_u32_e32 vcc, 0, v0
	s_and_b64 s[4:5], exec, vcc
	s_mov_b64 exec, s[4:5]
	s_cbranch_execz .LBB0_2163
	s_bcnt1_i32_b64 s4, s[16:17]
	v_mov_b32_e32 v0, 0
	v_mov_b32_e32 v1, s4
	global_atomic_add v0, v1, s[74:75] offset:512
.LBB0_2163:
	s_or_b64 exec, exec, s[0:1]
	s_waitcnt vmcnt(0)
	s_waitcnt vmcnt(0)
.LBB0_2164:
	s_andn2_saveexec_b64 s[0:1], s[14:15]
	s_cbranch_execz .LBB0_2184
	s_mov_b64 s[0:1], exec
	buffer_wbl2 sc1
	s_waitcnt lgkmcnt(0)
	s_waitcnt vmcnt(0)
	v_mbcnt_lo_u32_b32 v1, s0, 0
	v_mbcnt_hi_u32_b32 v1, s1, v1
	v_cmp_eq_u32_e32 vcc, 0, v1
	s_and_saveexec_b64 s[14:15], vcc
	s_cbranch_execz .LBB0_2167
	s_bcnt1_i32_b64 s0, s[0:1]
	v_mov_b32_e32 v2, 0x3000
	v_mov_b32_e32 v3, s0
	global_atomic_add v2, v2, v3, s[74:75] offset:1024 sc0

; #define PG8_STAGE(bufoff, gbase, voff) do { const unsigned long long gb_ = (unsigned long long)(gbase); _Pragma("unroll") for (int _i = 0; _i < 2; ++_i) { unsigned keep_; \
;         asm volatile("s_mov_b32 m0, %2\n\ts_nop 0\n\tglobal_load_lds_dwordx4 %0, %1" : : "v"((voff)[_i]), "s"(gb_), "s"((unsigned)(size_t)(lds + (bufoff) + ldsw + _i * 8192)) : "memory", "m0"); (void)keep_; } } while (0)
; #define PG8_WAIT_V(n) asm volatile("s_waitcnt vmcnt(" #n ")" ::: "memory")
; #define PG8_BAR __builtin_amdgcn_s_barrier()
; template <class Epi, class Sched, bool ALIGN_EPI = false, bool SP2 = false>
; __device__ __forceinline__ void gemm_phase(PG8_LAS unsigned char* lds, const Gemm g, const Sched& S, const Epi& E) {
;     ...
;     const unsigned ldsw = (unsigned)wid * 1024u;
;     const int aoff = lds_byte(wr * 64 + fr, fq * 8), boff = lds_byte(wc * 32 + fr, fq * 8);
;     ...
;     if constexpr (SP2) {
;         PG8_STAGE(PG8_SB(0, 0), cB, voffB); PG8_STAGE(PG8_SB(0, 1), cB + hstepB, voffB); PG8_STAGE(PG8_SA(0, 0), cA, voffA); PG8_STAGE(PG8_SA(0, 1), cA + hstepA, voffA);
;         if (wr == 1) PG8_BAR;
;         PG8_WAIT_V(2); PG8_BAR;
;         PG8_STAGE(PG8_SB(1, 0), cB + kstep, voffB); PG8_STAGE(PG8_SA(1, 0), cA + kstep, voffA); PG8_STAGE(PG8_SB(1, 1), cB + hstepB + kstep, voffB);
;         PG8_WAIT_V(6); PG8_BAR;
.LBB0_2218:
	v_bfe_u32 v4, v200, 4, 2
	v_and_b32_e32 v1, 15, v200
	v_lshlrev_b32_e32 v0, 4, v4
	v_lshlrev_b32_e32 v3, 2, v200
	s_and_b32 s61, s0, 3
	v_lshl_or_b32 v2, v1, 6, v0
	s_lshl_b32 s0, s1, 13
	v_and_b32_e32 v3, 32, v3
	s_waitcnt vmcnt(23)
	v_bitop3_b32 v6, v2, s0, v3 bitop3:0xde
	v_lshlrev_b32_e32 v2, 6, v200
	s_movk_i32 s0, 0x3c0
	s_lshl_b32 s5, s1, 6
	v_and_or_b32 v2, v2, s0, v0
	s_lshl_b32 s0, s61, 12
	s_add_u32 s24, s14, 0x200000
	s_addc_u32 s25, s15, 0
	s_add_u32 s14, s14, 0xa000000
	s_addc_u32 s15, s15, 0
	v_or_b32_e32 v136, s5, v1
	v_bitop3_b32 v7, s0, v2, v3 bitop3:0xf6
	s_add_u32 s0, s40, 0x80
	v_mov_b32_e32 v137, 0
	s_addc_u32 s1, s41, 0
	s_add_i32 s62, s53, 0x18000
	s_mov_b32 m0, s62
	s_nop 0
	global_load_lds_dwordx4 v173, s[0:1]
	s_add_i32 s63, s53, 0x1a000
	v_or_b32_e32 v2, 16, v136
	v_mov_b32_e32 v3, v137
	s_mov_b32 m0, s63
	s_nop 0
	global_load_lds_dwordx4 v175, s[0:1]
	s_add_u32 s0, s10, 0x80
	v_lshlrev_b64 v[140:141], 9, v[2:3]
	v_or_b32_e32 v2, 32, v136
	s_addc_u32 s1, s11, 0
	s_add_i32 s64, s53, 0x8000
	s_mov_b32 m0, s64
	s_nop 0
	global_load_lds_dwordx4 v172, s[0:1]
	s_add_i32 s65, s53, 0xa000
	v_lshlrev_b64 v[142:143], 9, v[2:3]
	v_or_b32_e32 v2, 48, v136
	s_mov_b32 m0, s65
	s_nop 0
	global_load_lds_dwordx4 v174, s[0:1]
	s_add_u32 s0, s40, 0x80080
	v_lshlrev_b64 v[144:145], 9, v[2:3]
	v_add_u32_e32 v2, 0x80, v136
	s_addc_u32 s1, s41, 0
	s_add_i32 s66, s53, 0x1c000
	s_add_i32 s67, s53, 0x1e000
	s_add_i32 s68, s53, 0xc000
	v_lshlrev_b64 v[146:147], 9, v[2:3]
	v_add_u32_e32 v2, 0x90, v136
	s_mov_b32 m0, s66
	s_nop 0
	global_load_lds_dwordx4 v173, s[0:1]
	s_cmpk_lt_u32 s4, 0x100
	v_lshlrev_b64 v[148:149], 9, v[2:3]
	v_add_u32_e32 v2, 0xa0, v136
	s_mov_b32 m0, s67
	s_nop 0
	global_load_lds_dwordx4 v175, s[0:1]
	s_cselect_b64 s[26:27], -1, 0
	v_lshlrev_b64 v[150:151], 9, v[2:3]
	v_add_u32_e32 v2, 0xb0, v136
	s_add_i32 s69, s53, 0xe000
	s_ashr_i32 s70, s33, 31
	s_ashr_i32 s71, s2, 31
	s_lshl_b32 s0, s61, 6
	v_lshlrev_b64 v[152:153], 9, v[2:3]
	v_mov_b32_e32 v2, 0xcf
	s_add_u32 s0, s49, s0
	v_bitop3_b32 v2, s5, v2, v1 bitop3:0xc8
	s_addc_u32 s1, s50, 0
	v_mov_b32_e32 v1, v137
	v_lshl_add_u64 v[154:155], s[0:1], 0, v[0:1]
	v_lshlrev_b32_e32 v0, 5, v4
	s_cmp_eq_u64 s[22:23], 0
	s_cbranch_scc1 .Lstag_skip_0
	s_barrier
.Lstag_skip_0:
	s_waitcnt vmcnt(8)
	s_barrier
	s_waitcnt vmcnt(6)
	v_lshl_add_u64 v[156:157], s[8:9], 0, v[0:1]
	v_add_u32_e32 v0, 0, v7
	v_lshlrev_b32_e32 v5, 3, v4
	v_add_u32_e32 v177, 0x10000, v0
	v_add_u32_e32 v178, 0x14000, v0
	v_add_u32_e32 v180, 0x18000, v0
	v_add_u32_e32 v181, 0x1c000, v0
	v_mbcnt_lo_u32_b32 v0, -1, 0
	v_cmp_eq_u32_e64 s[6:7], 0, v4
	v_lshlrev_b64 v[138:139], 9, v[136:137]
	v_lshl_add_u32 v137, v2, 2, s48
	v_lshl_or_b32 v176, s61, 5, v5
	v_mov_b64_e32 v[158:159], 0x200
	v_mov_b64_e32 v[160:161], 0x1ff
	v_add_u32_e32 v179, 0, v6
	v_mov_b32_e32 v182, 0x358637bd
	v_mbcnt_hi_u32_b32 v183, -1, v0
	s_mov_b32 s72, 0
	s_barrier
	s_branch .LBB0_2221

; __device__ __forceinline__ unsigned xb_add(unsigned* p, unsigned v) { return __hip_atomic_fetch_add(p, v, __ATOMIC_RELAXED, __HIP_MEMORY_SCOPE_AGENT); }
; __device__ __forceinline__ void xcd_barrier(const XcdBarrier& b) {
;     ...
;     if (threadIdx.x == 0) {
;         unsigned* bar = b.bar;
;         __builtin_amdgcn_s_waitcnt(0);
;         unsigned nloc = b.st[0], nx = b.st[1];
;         if (nloc == 0u) { xcd_barrier_complete(bar, b.x, nloc, nx); b.st[0] = nloc; b.st[1] = nx; }
;         const unsigned old = xb_add(&bar[XB_XSUB(b.x)], 1u);
;         const unsigned gen = old / nloc;
;         if (old + 1u == (gen + 1u) * nloc) {
.LBB0_2301:
	s_mov_b64 s[0:1], exec
	s_lshl_b32 s3, s3, 8
	v_mbcnt_lo_u32_b32 v1, s0, 0
	s_add_u32 s12, s74, s3
	v_mbcnt_hi_u32_b32 v1, s1, v1
	s_addc_u32 s13, s75, 0
	v_cmp_eq_u32_e32 vcc, 0, v1
	s_and_saveexec_b64 s[14:15], vcc
	s_cbranch_execz .LBB0_2303
	s_bcnt1_i32_b64 s0, s[0:1]
	v_mov_b32_e32 v3, 0x1000
	v_mov_b32_e32 v4, s0
	global_atomic_add v3, v3, v4, s[12:13] offset:1024 sc0
	buffer_inv sc1

; __device__ __forceinline__ unsigned xb_ld(unsigned* p)              { return __hip_atomic_load(p, __ATOMIC_RELAXED, __HIP_MEMORY_SCOPE_AGENT); }
; __device__ __forceinline__ unsigned xb_add(unsigned* p, unsigned v) { return __hip_atomic_fetch_add(p, v, __ATOMIC_RELAXED, __HIP_MEMORY_SCOPE_AGENT); }
; #define XB_SPIN(cond, bar) do { unsigned _sp = 0; while (cond) { __builtin_amdgcn_s_sleep(1); \
;     if ((++_sp & 255u) == 0u) { if (xb_ld(&(bar)[XB_TMO])) break; if (_sp > XB_SPIN_CAP) { atomicAdd(&(bar)[XB_TMO], 1u); break; } } } } while (0)
; __device__ __forceinline__ void xcd_barrier(const XcdBarrier& b) {
;     ...
;         if (old + 1u == (gen + 1u) * nloc) {
;             __builtin_amdgcn_fence(__ATOMIC_RELEASE, "agent");
;             asm volatile("s_waitcnt vmcnt(0)" ::: "memory");
;             const unsigned og = xb_add(&bar[XB_TOP], 1u);
;             const unsigned tg = og / nx;
;             if (og + 1u == (tg + 1u) * nx) xb_add(&bar[XB_TOPGEN], 1u);
;             else XB_SPIN(xb_ld(&bar[XB_TOPGEN]) == tg, bar);
;             __builtin_amdgcn_fence(__ATOMIC_ACQUIRE, "agent");
;             xb_add(&bar[XB_XGEN(b.x)], 1u);
;             asm volatile("s_waitcnt vmcnt(0)" ::: "memory");
;         } else {
;             XB_SPIN(xb_ld(&bar[XB_XGEN(b.x)]) == gen, bar);
;             __builtin_amdgcn_fence(__ATOMIC_ACQUIRE, "agent");
;             asm volatile("s_waitcnt vmcnt(0)" ::: "memory");
;         }
.LBB0_2313:
	s_or_b64 exec, exec, s[18:19]
	s_xor_b64 s[4:5], s[20:21], -1
	s_and_saveexec_b64 s[16:17], s[4:5]
	s_xor_b64 s[16:17], exec, s[16:17]
	s_cbranch_execz .LBB0_2316
	s_mov_b64 s[16:17], exec
	v_mbcnt_lo_u32_b32 v0, s16, 0
	v_mbcnt_hi_u32_b32 v0, s17, v0
	v_cmp_eq_u32_e32 vcc, 0, v0
	s_and_b64 s[4:5], exec, vcc
	s_mov_b64 exec, s[4:5]
	s_cbranch_execz .LBB0_2316
	s_bcnt1_i32_b64 s3, s[16:17]
	v_mov_b32_e32 v0, 0
	v_mov_b32_e32 v1, s3
	global_atomic_add v0, v1, s[74:75] offset:512
.LBB0_2316:
	s_or_b64 exec, exec, s[0:1]
	s_waitcnt vmcnt(0)
	s_waitcnt vmcnt(0)
.LBB0_2317:
	s_andn2_saveexec_b64 s[0:1], s[14:15]
	s_cbranch_execz .LBB0_2337
	s_mov_b64 s[0:1], exec
	buffer_wbl2 sc1
	s_waitcnt lgkmcnt(0)
	s_waitcnt vmcnt(0)
	v_mbcnt_lo_u32_b32 v1, s0, 0
	v_mbcnt_hi_u32_b32 v1, s1, v1
	v_cmp_eq_u32_e32 vcc, 0, v1
	s_and_saveexec_b64 s[14:15], vcc
	s_cbranch_execz .LBB0_2320
	s_bcnt1_i32_b64 s0, s[0:1]
	v_mov_b32_e32 v2, 0x3000
	v_mov_b32_e32 v3, s0
	global_atomic_add v2, v2, v3, s[74:75] offset:1024 sc0
